# RES GEMM epilogues (3 instances): residual loads batched ahead of FMAs/stores with counted vmcnt instead of 64 serialized load-wait-store round trips
# speedup vs baseline: 1.1087x; 1.0414x over previous
.LBB0_154:
	s_add_i32 s4, s15, 0xffff8000
	v_mov_b32_e32 v64, v182
	s_waitcnt vmcnt(0)
	s_waitcnt vmcnt(0) lgkmcnt(0)
	s_barrier
	s_and_b32 s16, s15, 0x8000
	s_and_b32 s17, s4, 0x8000
	v_or_b32_e32 v71, s17, v121
	v_lshrrev_b32_e32 v65, 4, v64
	v_ashrrev_i32_e32 v66, 3, v64
	v_add_u32_e32 v68, 0x100, v64
	v_lshl_add_u32 v67, v64, 4, s16
	v_add_u32_e32 v69, 0x200, v64
	v_add_u32_e32 v72, s0, v66
	v_bitop3_b32 v73, v65, 7, v64 bitop3:0x48
	v_ashrrev_i32_e32 v74, 3, v68
	s_add_u32 s10, s30, s8
	v_add_u32_e32 v70, 0x300, v64
	v_lshl_add_u32 v68, v68, 4, s16
	v_ashrrev_i32_e32 v75, 3, v69
	v_lshl_add_u32 v69, v69, 4, s16
	v_add_u32_e32 v77, 0x4000, v67
	v_add3_u32 v84, v71, v122, v123
	v_add3_u32 v80, v71, v124, v123
	v_mad_i64_i32 v[64:65], s[18:19], v72, s64, 0
	v_lshlrev_b32_e32 v81, 4, v73
	v_add_u32_e32 v71, s0, v74
	s_addc_u32 s11, s31, s9
	v_ashrrev_i32_e32 v76, 3, v70
	v_lshl_add_u32 v70, v70, 4, s16
	v_readfirstlane_b32 s5, v68
	v_add_u32_e32 v72, s0, v75
	v_readfirstlane_b32 s20, v69
	v_readfirstlane_b32 s22, v77
	v_add_u32_e32 v77, 0x4000, v68
	v_add_u32_e32 v79, 0x4000, v69
	v_or_b32_e32 v64, v64, v81
	v_mad_i64_i32 v[68:69], s[18:19], v71, s64, 0
	v_readfirstlane_b32 s4, v67
	v_add_u32_e32 v73, s0, v76
	v_readfirstlane_b32 s21, v70
	v_add_u32_e32 v83, 0x4000, v70
	v_mad_i64_i32 v[70:71], s[18:19], v72, s64, 0
	v_lshl_add_u64 v[64:65], s[10:11], 0, v[64:65]
	v_or_b32_e32 v68, v68, v81
	v_add_u32_e32 v66, s14, v66
	v_mad_i64_i32 v[72:73], s[18:19], v73, s64, 0
	v_or_b32_e32 v70, v70, v81
	v_lshl_add_u64 v[64:65], v[64:65], 0, s[88:89]
	v_lshl_add_u64 v[68:69], s[10:11], 0, v[68:69]
	s_mov_b32 m0, s4
	v_mad_i64_i32 v[66:67], s[18:19], v66, s64, 0
	v_add_u32_e32 v74, s14, v74
	v_or_b32_e32 v72, v72, v81
	v_lshl_add_u64 v[70:71], s[10:11], 0, v[70:71]
	global_load_lds_dwordx4 v[64:65], off
	v_lshl_add_u64 v[64:65], v[68:69], 0, s[88:89]
	s_mov_b32 m0, s5
	v_add_u32_e32 v78, s14, v75
	v_or_b32_e32 v66, v66, v81
	v_mad_i64_i32 v[74:75], s[18:19], v74, s64, 0
	v_lshl_add_u64 v[72:73], s[10:11], 0, v[72:73]
	v_lshl_add_u64 v[68:69], v[70:71], 0, s[88:89]
	global_load_lds_dwordx4 v[64:65], off
	s_mov_b32 m0, s20
	v_add_u32_e32 v82, s14, v76
	v_readfirstlane_b32 s23, v77
	v_mad_i64_i32 v[76:77], s[18:19], v78, s64, 0
	v_lshl_add_u64 v[66:67], s[10:11], 0, v[66:67]
	v_or_b32_e32 v74, v74, v81
	v_lshl_add_u64 v[70:71], v[72:73], 0, s[88:89]
	global_load_lds_dwordx4 v[68:69], off
	s_mov_b32 m0, s21
	v_readfirstlane_b32 s36, v79
	v_mad_i64_i32 v[78:79], s[18:19], v82, s64, 0
	v_or_b32_e32 v76, v76, v81
	v_lshl_add_u64 v[66:67], v[66:67], 0, s[78:79]
	v_lshl_add_u64 v[74:75], s[10:11], 0, v[74:75]
	global_load_lds_dwordx4 v[70:71], off
	s_mov_b32 m0, s22
	v_or_b32_e32 v78, v78, v81
	v_lshl_add_u64 v[76:77], s[10:11], 0, v[76:77]
	v_lshl_add_u64 v[72:73], v[74:75], 0, s[78:79]
	global_load_lds_dwordx4 v[66:67], off
	s_mov_b32 m0, s23
	v_readfirstlane_b32 s18, v83
	v_lshl_add_u64 v[78:79], s[10:11], 0, v[78:79]
	v_lshl_add_u64 v[74:75], v[76:77], 0, s[78:79]
	global_load_lds_dwordx4 v[72:73], off
	s_mov_b32 m0, s36
	v_lshl_add_u64 v[76:77], v[78:79], 0, s[78:79]
	global_load_lds_dwordx4 v[74:75], off
	s_mov_b32 m0, s18
	s_add_u32 s8, s8, 0x80
	global_load_lds_dwordx4 v[76:77], off
	ds_read_b128 v[64:67], v84
	ds_read_b128 v[68:71], v80 offset:16384
	ds_read_b128 v[72:75], v80 offset:18432
	ds_read_b128 v[76:79], v80 offset:20480
	ds_read_b128 v[80:83], v80 offset:22528
	s_waitcnt lgkmcnt(0)
	v_mfma_f32_16x16x32_f16 v[60:63], v[64:67], v[68:71], v[60:63]
	s_addc_u32 s9, s9, 0
	s_add_i32 s15, s15, 0x8000
	s_cmpk_eq_i32 s8, 0x1580
	v_mfma_f32_16x16x32_f16 v[56:59], v[64:67], v[72:75], v[56:59]
	v_mfma_f32_16x16x32_f16 v[52:55], v[64:67], v[76:79], v[52:55]
	v_mfma_f32_16x16x32_f16 v[48:51], v[64:67], v[80:83], v[48:51]
	ds_read_b128 v[64:67], v84 offset:2048
	s_waitcnt lgkmcnt(0)
	v_mfma_f32_16x16x32_f16 v[44:47], v[64:67], v[68:71], v[44:47]
	v_mfma_f32_16x16x32_f16 v[40:43], v[64:67], v[72:75], v[40:43]
	v_mfma_f32_16x16x32_f16 v[32:35], v[64:67], v[76:79], v[32:35]
	v_mfma_f32_16x16x32_f16 v[28:31], v[64:67], v[80:83], v[28:31]
	ds_read_b128 v[64:67], v84 offset:4096
	s_waitcnt lgkmcnt(0)
	v_mfma_f32_16x16x32_f16 v[24:27], v[64:67], v[68:71], v[24:27]
	v_mfma_f32_16x16x32_f16 v[20:23], v[64:67], v[72:75], v[20:23]
	v_mfma_f32_16x16x32_f16 v[16:19], v[64:67], v[76:79], v[16:19]
	v_mfma_f32_16x16x32_f16 v[12:15], v[64:67], v[80:83], v[12:15]
	ds_read_b128 v[64:67], v84 offset:6144
	s_waitcnt lgkmcnt(0)
	v_mfma_f32_16x16x32_f16 v[8:11], v[64:67], v[68:71], v[8:11]
	v_or_b32_e32 v68, s17, v125
	v_add3_u32 v84, v68, v122, v123
	v_add3_u32 v85, v68, v124, v123
	ds_read_b128 v[68:71], v84
	v_mfma_f32_16x16x32_f16 v[4:7], v[64:67], v[72:75], v[4:7]
	ds_read_b128 v[72:75], v85 offset:18432
	v_mfma_f32_16x16x32_f16 v[0:3], v[64:67], v[76:79], v[0:3]
	ds_read_b128 v[76:79], v85 offset:20480
	v_mfma_f32_16x16x32_f16 v[36:39], v[64:67], v[80:83], v[36:39]
	ds_read_b128 v[64:67], v85 offset:16384
	ds_read_b128 v[80:83], v85 offset:22528
	s_waitcnt lgkmcnt(1)
	v_mfma_f32_16x16x32_f16 v[60:63], v[68:71], v[64:67], v[60:63]
	v_mfma_f32_16x16x32_f16 v[56:59], v[68:71], v[72:75], v[56:59]
	v_mfma_f32_16x16x32_f16 v[52:55], v[68:71], v[76:79], v[52:55]
	s_waitcnt lgkmcnt(0)
	v_mfma_f32_16x16x32_f16 v[48:51], v[68:71], v[80:83], v[48:51]
	ds_read_b128 v[68:71], v84 offset:2048
	s_waitcnt lgkmcnt(0)
	v_mfma_f32_16x16x32_f16 v[44:47], v[68:71], v[64:67], v[44:47]
	v_mfma_f32_16x16x32_f16 v[40:43], v[68:71], v[72:75], v[40:43]
	v_mfma_f32_16x16x32_f16 v[32:35], v[68:71], v[76:79], v[32:35]
	v_mfma_f32_16x16x32_f16 v[28:31], v[68:71], v[80:83], v[28:31]
	ds_read_b128 v[68:71], v84 offset:4096
	s_waitcnt lgkmcnt(0)
	v_mfma_f32_16x16x32_f16 v[24:27], v[68:71], v[64:67], v[24:27]
	v_mfma_f32_16x16x32_f16 v[20:23], v[68:71], v[72:75], v[20:23]
	v_mfma_f32_16x16x32_f16 v[16:19], v[68:71], v[76:79], v[16:19]
	v_mfma_f32_16x16x32_f16 v[12:15], v[68:71], v[80:83], v[12:15]
	ds_read_b128 v[68:71], v84 offset:6144
	s_waitcnt lgkmcnt(0)
	v_mfma_f32_16x16x32_f16 v[8:11], v[68:71], v[64:67], v[8:11]
	v_mfma_f32_16x16x32_f16 v[4:7], v[68:71], v[72:75], v[4:7]
	v_mfma_f32_16x16x32_f16 v[0:3], v[68:71], v[76:79], v[0:3]
	v_mfma_f32_16x16x32_f16 v[36:39], v[68:71], v[80:83], v[36:39]
	s_cbranch_scc0 .LBB0_154
	v_add_u32_e32 v80, s16, v121
	v_add3_u32 v76, v80, v122, v123
	v_add3_u32 v92, v80, v124, v123
	s_waitcnt vmcnt(0)
	s_barrier
	ds_read_b128 v[64:67], v76
	ds_read_b128 v[68:71], v76 offset:2048
	ds_read_b128 v[72:75], v76 offset:4096
	ds_read_b128 v[76:79], v76 offset:6144
	ds_read_b128 v[80:83], v92 offset:16384
	ds_read_b128 v[84:87], v92 offset:18432
	ds_read_b128 v[88:91], v92 offset:20480
	ds_read_b128 v[92:95], v92 offset:22528
	s_waitcnt lgkmcnt(3)
	v_mfma_f32_16x16x32_f16 v[96:99], v[72:75], v[80:83], v[24:27]
	s_ashr_i32 s4, s0, 31
	s_lshr_b32 s4, s4, 19
	s_add_i32 s4, s0, s4
	s_waitcnt lgkmcnt(2)
	v_mfma_f32_16x16x32_f16 v[20:23], v[72:75], v[84:87], v[20:23]
	s_ashr_i32 s8, s4, 13
	s_add_i32 s4, s8, s12
	s_mul_hi_i32 s5, s4, 0x9000
	s_waitcnt lgkmcnt(1)
	v_mfma_f32_16x16x32_f16 v[16:19], v[72:75], v[88:91], v[16:19]
	s_mul_i32 s4, s4, 0x9000
	s_add_u32 s8, s50, s4
	s_addc_u32 s9, s51, s5
	s_waitcnt lgkmcnt(0)
	v_mfma_f32_16x16x32_f16 v[72:75], v[72:75], v[92:95], v[12:15]
	s_add_i32 s13, s13, s59
	s_cmpk_gt_i32 s13, 0x7ff
	s_nop 0
	v_add_u32_e32 v12, s16, v125
	v_add3_u32 v13, v12, v122, v123
	v_add3_u32 v12, v12, v124, v123
	v_mfma_f32_16x16x32_f16 v[60:63], v[64:67], v[80:83], v[60:63]
	v_mfma_f32_16x16x32_f16 v[56:59], v[64:67], v[84:87], v[56:59]
	v_mfma_f32_16x16x32_f16 v[52:55], v[64:67], v[88:91], v[52:55]
	v_mfma_f32_16x16x32_f16 v[48:51], v[64:67], v[92:95], v[48:51]
	v_mfma_f32_16x16x32_f16 v[64:67], v[68:71], v[80:83], v[44:47]
	v_mfma_f32_16x16x32_f16 v[40:43], v[68:71], v[84:87], v[40:43]
	v_mfma_f32_16x16x32_f16 v[32:35], v[68:71], v[88:91], v[32:35]
	v_mfma_f32_16x16x32_f16 v[68:71], v[68:71], v[92:95], v[28:31]
	v_mfma_f32_16x16x32_f16 v[80:83], v[76:79], v[80:83], v[8:11]
	v_mfma_f32_16x16x32_f16 v[84:87], v[76:79], v[84:87], v[4:7]
	v_mfma_f32_16x16x32_f16 v[0:3], v[76:79], v[88:91], v[0:3]
	v_mfma_f32_16x16x32_f16 v[76:79], v[76:79], v[92:95], v[36:39]
	s_nop 0
	ds_read_b128 v[4:7], v13
	ds_read_b128 v[8:11], v13 offset:2048
	ds_read_b128 v[88:91], v13 offset:4096
	ds_read_b128 v[92:95], v13 offset:6144
	ds_read_b128 v[100:103], v12 offset:16384
	ds_read_b128 v[104:107], v12 offset:18432
	ds_read_b128 v[108:111], v12 offset:20480
	ds_read_b128 v[116:119], v12 offset:22528
	s_waitcnt lgkmcnt(3)
	v_mfma_f32_16x16x32_f16 v[60:63], v[4:7], v[100:103], v[60:63]
	s_waitcnt lgkmcnt(2)
	v_mfma_f32_16x16x32_f16 v[44:47], v[4:7], v[104:107], v[56:59]
	s_waitcnt lgkmcnt(1)
	v_mfma_f32_16x16x32_f16 v[28:31], v[4:7], v[108:111], v[52:55]
	s_waitcnt lgkmcnt(0)
	v_mfma_f32_16x16x32_f16 v[12:15], v[4:7], v[116:119], v[48:51]
	v_mfma_f32_16x16x32_f16 v[52:55], v[88:91], v[100:103], v[96:99]
	v_mfma_f32_16x16x32_f16 v[36:39], v[88:91], v[104:107], v[20:23]
	v_mfma_f32_16x16x32_f16 v[20:23], v[88:91], v[108:111], v[16:19]
	v_mfma_f32_16x16x32_f16 v[4:7], v[88:91], v[116:119], v[72:75]
	v_add_u32_e32 v90, s0, v120
	v_or_b32_e32 v88, s14, v115
	v_ashrrev_i32_e32 v89, 31, v88
	v_mfma_f32_16x16x32_f16 v[56:59], v[8:11], v[100:103], v[64:67]
	v_ashrrev_i32_e32 v91, 31, v90
	v_or_b32_e32 v98, 33, v90
	v_ashrrev_i32_e32 v99, 31, v98
	v_or_b32_e32 v64, 48, v90
	v_ashrrev_i32_e32 v65, 31, v64
	v_mfma_f32_16x16x32_f16 v[40:43], v[8:11], v[104:107], v[40:43]
	v_lshlrev_b64 v[98:99], 10, v[98:99]
	v_lshl_add_u64 v[98:99], v[98:99], 0, v[88:89]
	v_mfma_f32_16x16x32_f16 v[24:27], v[8:11], v[108:111], v[32:35]
	v_mfma_f32_16x16x32_f16 v[32:35], v[92:95], v[104:107], v[84:87]
	v_lshlrev_b64 v[104:105], 10, v[64:65]
	v_lshl_add_u64 v[64:65], v[88:89], 2, s[8:9]
	v_add_co_u32_e32 v66, vcc, s48, v64
	v_mfma_f32_16x16x32_f16 v[8:11], v[8:11], v[116:119], v[68:71]
	s_nop 0
	v_addc_co_u32_e32 v67, vcc, 0, v65, vcc
	global_load_dword v64, v[66:67], off
	v_mfma_f32_16x16x32_f16 v[16:19], v[92:95], v[108:111], v[0:3]
	v_or_b32_e32 v106, 35, v90
	v_ashrrev_i32_e32 v107, 31, v106
	v_lshlrev_b64 v[106:107], 10, v[106:107]
	v_mfma_f32_16x16x32_f16 v[0:3], v[92:95], v[116:119], v[76:79]
	v_lshl_add_u64 v[106:107], v[106:107], 0, v[88:89]
	v_lshlrev_b64 v[108:109], 2, v[106:107]
	v_lshl_add_u64 v[106:107], s[2:3], 0, v[108:109]
	v_mfma_f32_16x16x32_f16 v[48:51], v[92:95], v[100:103], v[80:83]
	v_lshlrev_b32_e32 v68, 2, v88
	v_lshl_add_u32 v65, v90, 12, v68
	v_add_u32_e32 v69, 0x1000, v65
	v_add_u32_e32 v70, 0x3000, v65
	v_add_u32_e32 v71, 0x11000, v65
	v_add_u32_e32 v72, 0x13000, v65
	v_add_u32_e32 v73, 0x21000, v65
	v_add_u32_e32 v74, 0x23000, v65
	v_add_u32_e32 v75, 0x31000, v65
	v_add_u32_e32 v76, 0x33000, v65
	global_load_dword v77, v[66:67], off offset:0
	global_load_dword v78, v[66:67], off offset:64
	global_load_dword v79, v[66:67], off offset:128
	global_load_dword v80, v[66:67], off offset:192
	global_load_dword v81, v69, s[2:3] offset:-4096
	global_load_dword v82, v69, s[2:3] offset:0
	global_load_dword v83, v70, s[2:3] offset:-4096
	global_load_dword v84, v70, s[2:3] offset:0
	global_load_dword v85, v71, s[2:3] offset:-4096
	global_load_dword v86, v71, s[2:3] offset:0
	global_load_dword v87, v72, s[2:3] offset:-4096
	global_load_dword v89, v72, s[2:3] offset:0
	global_load_dword v91, v73, s[2:3] offset:-4096
	global_load_dword v92, v73, s[2:3] offset:0
	global_load_dword v93, v74, s[2:3] offset:-4096
	global_load_dword v94, v74, s[2:3] offset:0
	global_load_dword v95, v75, s[2:3] offset:-4096
	global_load_dword v96, v75, s[2:3] offset:0
	global_load_dword v97, v76, s[2:3] offset:-4096
	global_load_dword v98, v76, s[2:3] offset:0
	global_load_dword v99, v69, s[2:3] offset:-4032
	global_load_dword v100, v69, s[2:3] offset:64
	global_load_dword v101, v70, s[2:3] offset:-4032
	global_load_dword v102, v70, s[2:3] offset:64
	global_load_dword v103, v71, s[2:3] offset:-4032
	global_load_dword v104, v71, s[2:3] offset:64
	global_load_dword v105, v72, s[2:3] offset:-4032
	global_load_dword v106, v72, s[2:3] offset:64
	global_load_dword v107, v73, s[2:3] offset:-4032
	global_load_dword v108, v73, s[2:3] offset:64
	global_load_dword v109, v74, s[2:3] offset:-4032
	global_load_dword v110, v74, s[2:3] offset:64
	global_load_dword v111, v75, s[2:3] offset:-4032
	global_load_dword v112, v75, s[2:3] offset:64
	global_load_dword v116, v76, s[2:3] offset:-4032
	global_load_dword v117, v76, s[2:3] offset:64
	s_waitcnt vmcnt(32)
	v_add_f32_e32 v77, 1.0, v77
	v_add_f32_e32 v78, 1.0, v78
	v_add_f32_e32 v79, 1.0, v79
	v_add_f32_e32 v80, 1.0, v80
	v_mul_f32_e32 v77, 0.5, v77
	v_mul_f32_e32 v78, 0.5, v78
	v_mul_f32_e32 v79, 0.5, v79
	v_mul_f32_e32 v80, 0.5, v80
	s_waitcnt vmcnt(31)
	v_mul_f32_e32 v60, v60, v77
	v_fmac_f32_e32 v60, 0x3fb504f3, v81
	global_load_dword v81, v69, s[2:3] offset:-3968
	global_store_dword v69, v60, s[28:29] offset:-4096
	s_waitcnt vmcnt(32)
	v_mul_f32_e32 v61, v61, v77
	v_fmac_f32_e32 v61, 0x3fb504f3, v82
	global_load_dword v82, v69, s[2:3] offset:128
	global_store_dword v69, v61, s[28:29] offset:0
	s_waitcnt vmcnt(33)
	v_mul_f32_e32 v62, v62, v77
	v_fmac_f32_e32 v62, 0x3fb504f3, v83
	global_load_dword v83, v70, s[2:3] offset:-3968
	global_store_dword v70, v62, s[28:29] offset:-4096
	s_waitcnt vmcnt(34)
	v_mul_f32_e32 v63, v63, v77
	v_fmac_f32_e32 v63, 0x3fb504f3, v84
	global_load_dword v84, v70, s[2:3] offset:128
	global_store_dword v70, v63, s[28:29] offset:0
	s_waitcnt vmcnt(35)
	v_mul_f32_e32 v56, v56, v77
	v_fmac_f32_e32 v56, 0x3fb504f3, v85
	global_load_dword v85, v71, s[2:3] offset:-3968
	global_store_dword v71, v56, s[28:29] offset:-4096
	s_waitcnt vmcnt(36)
	v_mul_f32_e32 v57, v57, v77
	v_fmac_f32_e32 v57, 0x3fb504f3, v86
	global_load_dword v86, v71, s[2:3] offset:128
	global_store_dword v71, v57, s[28:29] offset:0
	s_waitcnt vmcnt(37)
	v_mul_f32_e32 v58, v58, v77
	v_fmac_f32_e32 v58, 0x3fb504f3, v87
	global_load_dword v87, v72, s[2:3] offset:-3968
	global_store_dword v72, v58, s[28:29] offset:-4096
	s_waitcnt vmcnt(38)
	v_mul_f32_e32 v59, v59, v77
	v_fmac_f32_e32 v59, 0x3fb504f3, v89
	global_load_dword v89, v72, s[2:3] offset:128
	global_store_dword v72, v59, s[28:29] offset:0
	s_waitcnt vmcnt(39)
	v_mul_f32_e32 v52, v52, v77
	v_fmac_f32_e32 v52, 0x3fb504f3, v91
	global_load_dword v91, v73, s[2:3] offset:-3968
	global_store_dword v73, v52, s[28:29] offset:-4096
	s_waitcnt vmcnt(40)
	v_mul_f32_e32 v53, v53, v77
	v_fmac_f32_e32 v53, 0x3fb504f3, v92
	global_load_dword v92, v73, s[2:3] offset:128
	global_store_dword v73, v53, s[28:29] offset:0
	s_waitcnt vmcnt(41)
	v_mul_f32_e32 v54, v54, v77
	v_fmac_f32_e32 v54, 0x3fb504f3, v93
	global_load_dword v93, v74, s[2:3] offset:-3968
	global_store_dword v74, v54, s[28:29] offset:-4096
	s_waitcnt vmcnt(42)
	v_mul_f32_e32 v55, v55, v77
	v_fmac_f32_e32 v55, 0x3fb504f3, v94
	global_load_dword v94, v74, s[2:3] offset:128
	global_store_dword v74, v55, s[28:29] offset:0
	s_waitcnt vmcnt(43)
	v_mul_f32_e32 v48, v48, v77
	v_fmac_f32_e32 v48, 0x3fb504f3, v95
	global_load_dword v95, v75, s[2:3] offset:-3968
	global_store_dword v75, v48, s[28:29] offset:-4096
	s_waitcnt vmcnt(44)
	v_mul_f32_e32 v49, v49, v77
	v_fmac_f32_e32 v49, 0x3fb504f3, v96
	global_load_dword v96, v75, s[2:3] offset:128
	global_store_dword v75, v49, s[28:29] offset:0
	s_waitcnt vmcnt(45)
	v_mul_f32_e32 v50, v50, v77
	v_fmac_f32_e32 v50, 0x3fb504f3, v97
	global_load_dword v97, v76, s[2:3] offset:-3968
	global_store_dword v76, v50, s[28:29] offset:-4096
	s_waitcnt vmcnt(46)
	v_mul_f32_e32 v51, v51, v77
	v_fmac_f32_e32 v51, 0x3fb504f3, v98
	global_load_dword v98, v76, s[2:3] offset:128
	global_store_dword v76, v51, s[28:29] offset:0
	s_waitcnt vmcnt(47)
	v_mul_f32_e32 v44, v44, v78
	v_fmac_f32_e32 v44, 0x3fb504f3, v99
	global_load_dword v99, v69, s[2:3] offset:-3904
	global_store_dword v69, v44, s[28:29] offset:-4032
	s_waitcnt vmcnt(48)
	v_mul_f32_e32 v45, v45, v78
	v_fmac_f32_e32 v45, 0x3fb504f3, v100
	global_load_dword v100, v69, s[2:3] offset:192
	global_store_dword v69, v45, s[28:29] offset:64
	s_waitcnt vmcnt(49)
	v_mul_f32_e32 v46, v46, v78
	v_fmac_f32_e32 v46, 0x3fb504f3, v101
	global_load_dword v101, v70, s[2:3] offset:-3904
	global_store_dword v70, v46, s[28:29] offset:-4032
	s_waitcnt vmcnt(50)
	v_mul_f32_e32 v47, v47, v78
	v_fmac_f32_e32 v47, 0x3fb504f3, v102
	global_load_dword v102, v70, s[2:3] offset:192
	global_store_dword v70, v47, s[28:29] offset:64
	s_waitcnt vmcnt(51)
	v_mul_f32_e32 v40, v40, v78
	v_fmac_f32_e32 v40, 0x3fb504f3, v103
	global_load_dword v103, v71, s[2:3] offset:-3904
	global_store_dword v71, v40, s[28:29] offset:-4032
	s_waitcnt vmcnt(52)
	v_mul_f32_e32 v41, v41, v78
	v_fmac_f32_e32 v41, 0x3fb504f3, v104
	global_load_dword v104, v71, s[2:3] offset:192
	global_store_dword v71, v41, s[28:29] offset:64
	s_waitcnt vmcnt(53)
	v_mul_f32_e32 v42, v42, v78
	v_fmac_f32_e32 v42, 0x3fb504f3, v105
	global_load_dword v105, v72, s[2:3] offset:-3904
	global_store_dword v72, v42, s[28:29] offset:-4032
	s_waitcnt vmcnt(54)
	v_mul_f32_e32 v43, v43, v78
	v_fmac_f32_e32 v43, 0x3fb504f3, v106
	global_load_dword v106, v72, s[2:3] offset:192
	global_store_dword v72, v43, s[28:29] offset:64
	s_waitcnt vmcnt(55)
	v_mul_f32_e32 v36, v36, v78
	v_fmac_f32_e32 v36, 0x3fb504f3, v107
	global_load_dword v107, v73, s[2:3] offset:-3904
	global_store_dword v73, v36, s[28:29] offset:-4032
	s_waitcnt vmcnt(56)
	v_mul_f32_e32 v37, v37, v78
	v_fmac_f32_e32 v37, 0x3fb504f3, v108
	global_load_dword v108, v73, s[2:3] offset:192
	global_store_dword v73, v37, s[28:29] offset:64
	s_waitcnt vmcnt(57)
	v_mul_f32_e32 v38, v38, v78
	v_fmac_f32_e32 v38, 0x3fb504f3, v109
	global_load_dword v109, v74, s[2:3] offset:-3904
	global_store_dword v74, v38, s[28:29] offset:-4032
	s_waitcnt vmcnt(58)
	v_mul_f32_e32 v39, v39, v78
	v_fmac_f32_e32 v39, 0x3fb504f3, v110
	global_load_dword v110, v74, s[2:3] offset:192
	global_store_dword v74, v39, s[28:29] offset:64
	s_waitcnt vmcnt(59)
	v_mul_f32_e32 v32, v32, v78
	v_fmac_f32_e32 v32, 0x3fb504f3, v111
	global_load_dword v111, v75, s[2:3] offset:-3904
	global_store_dword v75, v32, s[28:29] offset:-4032
	s_waitcnt vmcnt(60)
	v_mul_f32_e32 v33, v33, v78
	v_fmac_f32_e32 v33, 0x3fb504f3, v112
	global_load_dword v112, v75, s[2:3] offset:192
	global_store_dword v75, v33, s[28:29] offset:64
	s_waitcnt vmcnt(61)
	v_mul_f32_e32 v34, v34, v78
	v_fmac_f32_e32 v34, 0x3fb504f3, v116
	global_load_dword v116, v76, s[2:3] offset:-3904
	global_store_dword v76, v34, s[28:29] offset:-4032
	s_waitcnt vmcnt(62)
	v_mul_f32_e32 v35, v35, v78
	v_fmac_f32_e32 v35, 0x3fb504f3, v117
	global_load_dword v117, v76, s[2:3] offset:192
	global_store_dword v76, v35, s[28:29] offset:64
	s_waitcnt vmcnt(63)
	v_mul_f32_e32 v28, v28, v79
	v_fmac_f32_e32 v28, 0x3fb504f3, v81
	global_store_dword v69, v28, s[28:29] offset:-3968
	s_waitcnt vmcnt(62)
	v_mul_f32_e32 v29, v29, v79
	v_fmac_f32_e32 v29, 0x3fb504f3, v82
	global_store_dword v69, v29, s[28:29] offset:128
	s_waitcnt vmcnt(61)
	v_mul_f32_e32 v30, v30, v79
	v_fmac_f32_e32 v30, 0x3fb504f3, v83
	global_store_dword v70, v30, s[28:29] offset:-3968
	s_waitcnt vmcnt(60)
	v_mul_f32_e32 v31, v31, v79
	v_fmac_f32_e32 v31, 0x3fb504f3, v84
	global_store_dword v70, v31, s[28:29] offset:128
	s_waitcnt vmcnt(59)
	v_mul_f32_e32 v24, v24, v79
	v_fmac_f32_e32 v24, 0x3fb504f3, v85
	global_store_dword v71, v24, s[28:29] offset:-3968
	s_waitcnt vmcnt(58)
	v_mul_f32_e32 v25, v25, v79
	v_fmac_f32_e32 v25, 0x3fb504f3, v86
	global_store_dword v71, v25, s[28:29] offset:128
	s_waitcnt vmcnt(57)
	v_mul_f32_e32 v26, v26, v79
	v_fmac_f32_e32 v26, 0x3fb504f3, v87
	global_store_dword v72, v26, s[28:29] offset:-3968
	s_waitcnt vmcnt(56)
	v_mul_f32_e32 v27, v27, v79
	v_fmac_f32_e32 v27, 0x3fb504f3, v89
	global_store_dword v72, v27, s[28:29] offset:128
	s_waitcnt vmcnt(55)
	v_mul_f32_e32 v20, v20, v79
	v_fmac_f32_e32 v20, 0x3fb504f3, v91
	global_store_dword v73, v20, s[28:29] offset:-3968
	s_waitcnt vmcnt(54)
	v_mul_f32_e32 v21, v21, v79
	v_fmac_f32_e32 v21, 0x3fb504f3, v92
	global_store_dword v73, v21, s[28:29] offset:128
	s_waitcnt vmcnt(53)
	v_mul_f32_e32 v22, v22, v79
	v_fmac_f32_e32 v22, 0x3fb504f3, v93
	global_store_dword v74, v22, s[28:29] offset:-3968
	s_waitcnt vmcnt(52)
	v_mul_f32_e32 v23, v23, v79
	v_fmac_f32_e32 v23, 0x3fb504f3, v94
	global_store_dword v74, v23, s[28:29] offset:128
	s_waitcnt vmcnt(51)
	v_mul_f32_e32 v16, v16, v79
	v_fmac_f32_e32 v16, 0x3fb504f3, v95
	global_store_dword v75, v16, s[28:29] offset:-3968
	s_waitcnt vmcnt(50)
	v_mul_f32_e32 v17, v17, v79
	v_fmac_f32_e32 v17, 0x3fb504f3, v96
	global_store_dword v75, v17, s[28:29] offset:128
	s_waitcnt vmcnt(49)
	v_mul_f32_e32 v18, v18, v79
	v_fmac_f32_e32 v18, 0x3fb504f3, v97
	global_store_dword v76, v18, s[28:29] offset:-3968
	s_waitcnt vmcnt(48)
	v_mul_f32_e32 v19, v19, v79
	v_fmac_f32_e32 v19, 0x3fb504f3, v98
	global_store_dword v76, v19, s[28:29] offset:128
	s_waitcnt vmcnt(47)
	v_mul_f32_e32 v12, v12, v80
	v_fmac_f32_e32 v12, 0x3fb504f3, v99
	global_store_dword v69, v12, s[28:29] offset:-3904
	s_waitcnt vmcnt(46)
	v_mul_f32_e32 v13, v13, v80
	v_fmac_f32_e32 v13, 0x3fb504f3, v100
	global_store_dword v69, v13, s[28:29] offset:192
	s_waitcnt vmcnt(45)
	v_mul_f32_e32 v14, v14, v80
	v_fmac_f32_e32 v14, 0x3fb504f3, v101
	global_store_dword v70, v14, s[28:29] offset:-3904
	s_waitcnt vmcnt(44)
	v_mul_f32_e32 v15, v15, v80
	v_fmac_f32_e32 v15, 0x3fb504f3, v102
	global_store_dword v70, v15, s[28:29] offset:192
	s_waitcnt vmcnt(43)
	v_mul_f32_e32 v8, v8, v80
	v_fmac_f32_e32 v8, 0x3fb504f3, v103
	global_store_dword v71, v8, s[28:29] offset:-3904
	s_waitcnt vmcnt(42)
	v_mul_f32_e32 v9, v9, v80
	v_fmac_f32_e32 v9, 0x3fb504f3, v104
	global_store_dword v71, v9, s[28:29] offset:192
	s_waitcnt vmcnt(41)
	v_mul_f32_e32 v10, v10, v80
	v_fmac_f32_e32 v10, 0x3fb504f3, v105
	global_store_dword v72, v10, s[28:29] offset:-3904
	s_waitcnt vmcnt(40)
	v_mul_f32_e32 v11, v11, v80
	v_fmac_f32_e32 v11, 0x3fb504f3, v106
	global_store_dword v72, v11, s[28:29] offset:192
	s_waitcnt vmcnt(39)
	v_mul_f32_e32 v4, v4, v80
	v_fmac_f32_e32 v4, 0x3fb504f3, v107
	global_store_dword v73, v4, s[28:29] offset:-3904
	s_waitcnt vmcnt(38)
	v_mul_f32_e32 v5, v5, v80
	v_fmac_f32_e32 v5, 0x3fb504f3, v108
	global_store_dword v73, v5, s[28:29] offset:192
	s_waitcnt vmcnt(37)
	v_mul_f32_e32 v6, v6, v80
	v_fmac_f32_e32 v6, 0x3fb504f3, v109
	global_store_dword v74, v6, s[28:29] offset:-3904
	s_waitcnt vmcnt(36)
	v_mul_f32_e32 v7, v7, v80
	v_fmac_f32_e32 v7, 0x3fb504f3, v110
	global_store_dword v74, v7, s[28:29] offset:192
	s_waitcnt vmcnt(35)
	v_mul_f32_e32 v0, v0, v80
	v_fmac_f32_e32 v0, 0x3fb504f3, v111
	global_store_dword v75, v0, s[28:29] offset:-3904
	s_waitcnt vmcnt(34)
	v_mul_f32_e32 v1, v1, v80
	v_fmac_f32_e32 v1, 0x3fb504f3, v112
	global_store_dword v75, v1, s[28:29] offset:192
	s_waitcnt vmcnt(33)
	v_mul_f32_e32 v2, v2, v80
	v_fmac_f32_e32 v2, 0x3fb504f3, v116
	global_store_dword v76, v2, s[28:29] offset:-3904
	s_waitcnt vmcnt(32)
	v_mul_f32_e32 v3, v3, v80
	v_fmac_f32_e32 v3, 0x3fb504f3, v117
	global_store_dword v76, v3, s[28:29] offset:192
	s_cbranch_scc0 .LBB0_153

.LBB0_601:
	s_add_i32 s4, s13, 0xffff8000
	v_mov_b32_e32 v64, v182
	s_waitcnt vmcnt(0)
	s_waitcnt vmcnt(0) lgkmcnt(0)
	s_barrier
	s_and_b32 s14, s13, 0x8000
	s_and_b32 s15, s4, 0x8000
	v_or_b32_e32 v71, s15, v86
	v_lshrrev_b32_e32 v65, 4, v64
	v_ashrrev_i32_e32 v66, 3, v64
	v_add_u32_e32 v68, 0x100, v64
	v_lshl_add_u32 v67, v64, 4, s14
	v_add_u32_e32 v69, 0x200, v64
	v_add_u32_e32 v72, s0, v66
	v_bitop3_b32 v65, v65, 7, v64 bitop3:0x48
	v_ashrrev_i32_e32 v73, 3, v68
	s_add_u32 s8, s30, s2
	v_add_u32_e32 v70, 0x300, v64
	v_readfirstlane_b32 s16, v67
	v_lshl_add_u32 v74, v68, 4, s14
	v_ashrrev_i32_e32 v75, 3, v69
	v_add_u32_e32 v64, s12, v66
	v_add_u32_e32 v68, 0x4000, v67
	v_add3_u32 v91, v71, v87, v88
	v_add3_u32 v80, v71, v89, v88
	v_mad_i64_i32 v[66:67], s[4:5], v72, s63, 0
	v_lshlrev_b32_e32 v81, 4, v65
	v_add_u32_e32 v71, s0, v73
	s_addc_u32 s9, s31, s3
	v_ashrrev_i32_e32 v76, 3, v70
	v_lshl_add_u32 v77, v70, 4, s14
	v_readfirstlane_b32 s17, v74
	v_add_u32_e32 v78, s0, v75
	v_readfirstlane_b32 s20, v68
	v_add_u32_e32 v68, s12, v73
	v_add_u32_e32 v73, 0x4000, v74
	v_add_u32_e32 v70, s12, v75
	v_or_b32_e32 v66, v66, v81
	v_mad_i64_i32 v[74:75], s[4:5], v71, s63, 0
	v_add_u32_e32 v79, s0, v76
	v_readfirstlane_b32 s19, v77
	v_add_u32_e32 v72, s12, v76
	v_add_u32_e32 v83, 0x4000, v77
	v_mad_i64_i32 v[76:77], s[4:5], v78, s63, 0
	v_lshl_add_u64 v[66:67], s[8:9], 0, v[66:67]
	v_or_b32_e32 v74, v74, v81
	v_lshl_add_u32 v69, v69, 4, s14
	v_ashrrev_i32_e32 v65, 31, v64
	v_mad_i64_i32 v[78:79], s[4:5], v79, s63, 0
	v_or_b32_e32 v76, v76, v81
	v_lshl_add_u64 v[66:67], v[66:67], 0, s[80:81]
	v_lshl_add_u64 v[74:75], s[8:9], 0, v[74:75]
	s_mov_b32 m0, s16
	v_readfirstlane_b32 s18, v69
	v_add_u32_e32 v82, 0x4000, v69
	v_lshlrev_b64 v[64:65], 11, v[64:65]
	v_ashrrev_i32_e32 v69, 31, v68
	v_or_b32_e32 v78, v78, v81
	v_lshl_add_u64 v[76:77], s[8:9], 0, v[76:77]
	global_load_lds_dwordx4 v[66:67], off
	v_lshl_add_u64 v[66:67], v[74:75], 0, s[80:81]
	s_mov_b32 m0, s17
	v_ashrrev_i32_e32 v71, 31, v70
	v_or_b32_e32 v64, v64, v81
	v_lshlrev_b64 v[68:69], 11, v[68:69]
	v_lshl_add_u64 v[78:79], s[8:9], 0, v[78:79]
	v_lshl_add_u64 v[74:75], v[76:77], 0, s[80:81]
	global_load_lds_dwordx4 v[66:67], off
	s_mov_b32 m0, s18
	v_readfirstlane_b32 s4, v73
	v_ashrrev_i32_e32 v73, 31, v72
	v_lshlrev_b64 v[70:71], 11, v[70:71]
	v_lshl_add_u64 v[64:65], s[8:9], 0, v[64:65]
	v_or_b32_e32 v68, v68, v81
	v_lshl_add_u64 v[76:77], v[78:79], 0, s[80:81]
	global_load_lds_dwordx4 v[74:75], off
	s_mov_b32 m0, s19
	v_lshlrev_b64 v[72:73], 11, v[72:73]
	v_or_b32_e32 v70, v70, v81
	v_lshl_add_u64 v[64:65], v[64:65], 0, s[82:83]
	v_lshl_add_u64 v[68:69], s[8:9], 0, v[68:69]
	global_load_lds_dwordx4 v[76:77], off
	s_mov_b32 m0, s20
	v_readfirstlane_b32 s5, v82
	v_or_b32_e32 v72, v72, v81
	v_lshl_add_u64 v[70:71], s[8:9], 0, v[70:71]
	v_lshl_add_u64 v[66:67], v[68:69], 0, s[82:83]
	global_load_lds_dwordx4 v[64:65], off
	s_mov_b32 m0, s4
	v_readfirstlane_b32 s21, v83
	v_lshl_add_u64 v[72:73], s[8:9], 0, v[72:73]
	v_lshl_add_u64 v[68:69], v[70:71], 0, s[82:83]
	global_load_lds_dwordx4 v[66:67], off
	s_mov_b32 m0, s5
	v_lshl_add_u64 v[70:71], v[72:73], 0, s[82:83]
	global_load_lds_dwordx4 v[68:69], off
	s_mov_b32 m0, s21
	s_add_u32 s2, s2, 0x80
	global_load_lds_dwordx4 v[70:71], off
	ds_read_b128 v[64:67], v91
	ds_read_b128 v[68:71], v80 offset:16384
	ds_read_b128 v[72:75], v80 offset:18432
	ds_read_b128 v[76:79], v80 offset:20480
	ds_read_b128 v[80:83], v80 offset:22528
	s_waitcnt lgkmcnt(0)
	v_mfma_f32_16x16x32_f16 v[60:63], v[64:67], v[68:71], v[60:63]
	s_addc_u32 s3, s3, 0
	s_add_i32 s13, s13, 0x8000
	s_cmpk_eq_i32 s2, 0x780
	v_mfma_f32_16x16x32_f16 v[56:59], v[64:67], v[72:75], v[56:59]
	v_mfma_f32_16x16x32_f16 v[52:55], v[64:67], v[76:79], v[52:55]
	v_mfma_f32_16x16x32_f16 v[48:51], v[64:67], v[80:83], v[48:51]
	ds_read_b128 v[64:67], v91 offset:2048
	s_waitcnt lgkmcnt(0)
	v_mfma_f32_16x16x32_f16 v[44:47], v[64:67], v[68:71], v[44:47]
	v_mfma_f32_16x16x32_f16 v[40:43], v[64:67], v[72:75], v[40:43]
	v_mfma_f32_16x16x32_f16 v[36:39], v[64:67], v[76:79], v[36:39]
	v_mfma_f32_16x16x32_f16 v[32:35], v[64:67], v[80:83], v[32:35]
	ds_read_b128 v[64:67], v91 offset:4096
	s_waitcnt lgkmcnt(0)
	v_mfma_f32_16x16x32_f16 v[24:27], v[64:67], v[68:71], v[24:27]
	v_mfma_f32_16x16x32_f16 v[20:23], v[64:67], v[72:75], v[20:23]
	v_mfma_f32_16x16x32_f16 v[16:19], v[64:67], v[76:79], v[16:19]
	v_mfma_f32_16x16x32_f16 v[12:15], v[64:67], v[80:83], v[12:15]
	ds_read_b128 v[64:67], v91 offset:6144
	s_waitcnt lgkmcnt(0)
	v_mfma_f32_16x16x32_f16 v[8:11], v[64:67], v[68:71], v[8:11]
	v_or_b32_e32 v68, s15, v90
	v_add3_u32 v91, v68, v87, v88
	v_add3_u32 v92, v68, v89, v88
	ds_read_b128 v[68:71], v91
	v_mfma_f32_16x16x32_f16 v[4:7], v[64:67], v[72:75], v[4:7]
	ds_read_b128 v[72:75], v92 offset:18432
	v_mfma_f32_16x16x32_f16 v[0:3], v[64:67], v[76:79], v[0:3]
	ds_read_b128 v[76:79], v92 offset:20480
	v_mfma_f32_16x16x32_f16 v[28:31], v[64:67], v[80:83], v[28:31]
	ds_read_b128 v[64:67], v92 offset:16384
	ds_read_b128 v[80:83], v92 offset:22528
	s_waitcnt lgkmcnt(1)
	v_mfma_f32_16x16x32_f16 v[60:63], v[68:71], v[64:67], v[60:63]
	v_mfma_f32_16x16x32_f16 v[56:59], v[68:71], v[72:75], v[56:59]
	v_mfma_f32_16x16x32_f16 v[52:55], v[68:71], v[76:79], v[52:55]
	s_waitcnt lgkmcnt(0)
	v_mfma_f32_16x16x32_f16 v[48:51], v[68:71], v[80:83], v[48:51]
	ds_read_b128 v[68:71], v91 offset:2048
	s_waitcnt lgkmcnt(0)
	v_mfma_f32_16x16x32_f16 v[44:47], v[68:71], v[64:67], v[44:47]
	v_mfma_f32_16x16x32_f16 v[40:43], v[68:71], v[72:75], v[40:43]
	v_mfma_f32_16x16x32_f16 v[36:39], v[68:71], v[76:79], v[36:39]
	v_mfma_f32_16x16x32_f16 v[32:35], v[68:71], v[80:83], v[32:35]
	ds_read_b128 v[68:71], v91 offset:4096
	s_waitcnt lgkmcnt(0)
	v_mfma_f32_16x16x32_f16 v[24:27], v[68:71], v[64:67], v[24:27]
	v_mfma_f32_16x16x32_f16 v[20:23], v[68:71], v[72:75], v[20:23]
	v_mfma_f32_16x16x32_f16 v[16:19], v[68:71], v[76:79], v[16:19]
	v_mfma_f32_16x16x32_f16 v[12:15], v[68:71], v[80:83], v[12:15]
	ds_read_b128 v[68:71], v91 offset:6144
	s_waitcnt lgkmcnt(0)
	v_mfma_f32_16x16x32_f16 v[8:11], v[68:71], v[64:67], v[8:11]
	v_mfma_f32_16x16x32_f16 v[4:7], v[68:71], v[72:75], v[4:7]
	v_mfma_f32_16x16x32_f16 v[0:3], v[68:71], v[76:79], v[0:3]
	v_mfma_f32_16x16x32_f16 v[28:31], v[68:71], v[80:83], v[28:31]
	s_cbranch_scc0 .LBB0_601
	v_add_u32_e32 v80, s14, v86
	v_add3_u32 v76, v80, v87, v88
	v_add3_u32 v91, v80, v89, v88
	s_waitcnt vmcnt(0)
	s_barrier
	ds_read_b128 v[64:67], v76
	ds_read_b128 v[68:71], v76 offset:2048
	ds_read_b128 v[72:75], v76 offset:4096
	ds_read_b128 v[76:79], v76 offset:6144
	ds_read_b128 v[80:83], v91 offset:16384
	ds_read_b128 v[92:95], v91 offset:18432
	ds_read_b128 v[96:99], v91 offset:20480
	ds_read_b128 v[100:103], v91 offset:22528
	s_waitcnt lgkmcnt(3)
	v_mfma_f32_16x16x32_f16 v[60:63], v[64:67], v[80:83], v[60:63]
	s_ashr_i32 s2, s0, 31
	s_lshr_b32 s2, s2, 19
	s_add_i32 s2, s0, s2
	s_waitcnt lgkmcnt(2)
	v_mfma_f32_16x16x32_f16 v[56:59], v[64:67], v[92:95], v[56:59]
	s_ashr_i32 s2, s2, 13
	s_add_i32 s2, s2, s10
	s_mul_hi_i32 s3, s2, 0x9000
	s_waitcnt lgkmcnt(1)
	v_mfma_f32_16x16x32_f16 v[52:55], v[64:67], v[96:99], v[52:55]
	s_mul_i32 s2, s2, 0x9000
	s_add_u32 s2, s50, s2
	s_addc_u32 s3, s51, s3
	s_waitcnt lgkmcnt(0)
	v_mfma_f32_16x16x32_f16 v[48:51], v[64:67], v[100:103], v[48:51]
	s_add_i32 s11, s11, s59
	s_cmpk_gt_i32 s11, 0x7ff
	v_mfma_f32_16x16x32_f16 v[64:67], v[68:71], v[80:83], v[44:47]
	v_mfma_f32_16x16x32_f16 v[40:43], v[68:71], v[92:95], v[40:43]
	v_mfma_f32_16x16x32_f16 v[36:39], v[68:71], v[96:99], v[36:39]
	v_mfma_f32_16x16x32_f16 v[32:35], v[68:71], v[100:103], v[32:35]
	v_mfma_f32_16x16x32_f16 v[68:71], v[72:75], v[80:83], v[24:27]
	v_mfma_f32_16x16x32_f16 v[20:23], v[72:75], v[92:95], v[20:23]
	v_mfma_f32_16x16x32_f16 v[16:19], v[72:75], v[96:99], v[16:19]
	v_mfma_f32_16x16x32_f16 v[72:75], v[72:75], v[100:103], v[12:15]
	s_nop 2
	v_add_u32_e32 v12, s14, v90
	v_add3_u32 v13, v12, v87, v88
	v_add3_u32 v12, v12, v89, v88
	v_mfma_f32_16x16x32_f16 v[80:83], v[76:79], v[80:83], v[8:11]
	v_mfma_f32_16x16x32_f16 v[92:95], v[76:79], v[92:95], v[4:7]
	v_mfma_f32_16x16x32_f16 v[0:3], v[76:79], v[96:99], v[0:3]
	v_mfma_f32_16x16x32_f16 v[76:79], v[76:79], v[100:103], v[28:31]
	s_nop 0
	ds_read_b128 v[4:7], v13
	ds_read_b128 v[8:11], v13 offset:2048
	ds_read_b128 v[96:99], v13 offset:4096
	ds_read_b128 v[100:103], v13 offset:6144
	ds_read_b128 v[104:107], v12 offset:16384
	ds_read_b128 v[108:111], v12 offset:18432
	ds_read_b128 v[116:119], v12 offset:20480
	ds_read_b128 v[120:123], v12 offset:22528
	s_waitcnt lgkmcnt(1)
	v_mfma_f32_16x16x32_f16 v[28:31], v[4:7], v[116:119], v[52:55]
	v_mfma_f32_16x16x32_f16 v[52:55], v[8:11], v[104:107], v[64:67]
	s_nop 2
	v_or_b32_e32 v64, s12, v84
	v_ashrrev_i32_e32 v65, 31, v64
	v_mfma_f32_16x16x32_f16 v[60:63], v[4:7], v[104:107], v[60:63]
	v_mfma_f32_16x16x32_f16 v[44:47], v[4:7], v[108:111], v[56:59]
	s_waitcnt lgkmcnt(0)
	v_mfma_f32_16x16x32_f16 v[12:15], v[4:7], v[120:123], v[48:51]
	v_mfma_f32_16x16x32_f16 v[24:27], v[8:11], v[116:119], v[36:39]
	v_mfma_f32_16x16x32_f16 v[56:59], v[96:99], v[104:107], v[68:71]
	v_mfma_f32_16x16x32_f16 v[36:39], v[96:99], v[108:111], v[20:23]
	v_mfma_f32_16x16x32_f16 v[20:23], v[96:99], v[116:119], v[16:19]
	v_mfma_f32_16x16x32_f16 v[4:7], v[96:99], v[120:123], v[72:75]
	v_lshlrev_b64 v[96:97], 2, v[64:65]
	v_lshl_add_u64 v[64:65], s[2:3], 0, v[96:97]
	v_mfma_f32_16x16x32_f16 v[40:43], v[8:11], v[108:111], v[40:43]
	v_mfma_f32_16x16x32_f16 v[8:11], v[8:11], v[120:123], v[32:35]
	v_mfma_f32_16x16x32_f16 v[32:35], v[100:103], v[108:111], v[92:95]
	s_nop 2
	v_add_u32_e32 v92, s0, v85
	s_movk_i32 s0, 0x5000
	v_mfma_f32_16x16x32_f16 v[48:51], v[100:103], v[104:107], v[80:83]
	v_ashrrev_i32_e32 v93, 31, v92
	v_or_b32_e32 v94, 48, v92
	v_ashrrev_i32_e32 v95, 31, v94
	v_add_co_u32_e32 v80, vcc, s0, v64
	v_mfma_f32_16x16x32_f16 v[16:19], v[100:103], v[116:119], v[0:3]
	s_nop 0
	v_addc_co_u32_e32 v81, vcc, 0, v65, vcc
	global_load_dword v64, v[80:81], off
	v_mfma_f32_16x16x32_f16 v[0:3], v[100:103], v[120:123], v[76:79]
	v_lshl_add_u32 v65, v92, 12, v96
	v_add_u32_e32 v66, 0x1000, v65
	v_add_u32_e32 v67, 0x3000, v65
	v_add_u32_e32 v68, 0x11000, v65
	v_add_u32_e32 v69, 0x13000, v65
	v_add_u32_e32 v70, 0x21000, v65
	v_add_u32_e32 v71, 0x23000, v65
	v_add_u32_e32 v72, 0x31000, v65
	v_add_u32_e32 v73, 0x33000, v65
	global_load_dword v74, v[80:81], off offset:0
	global_load_dword v75, v[80:81], off offset:64
	global_load_dword v76, v[80:81], off offset:128
	global_load_dword v77, v[80:81], off offset:192
	global_load_dword v78, v66, s[28:29] offset:-4096
	global_load_dword v79, v66, s[28:29] offset:0
	global_load_dword v82, v67, s[28:29] offset:-4096
	global_load_dword v83, v67, s[28:29] offset:0
	global_load_dword v91, v68, s[28:29] offset:-4096
	global_load_dword v93, v68, s[28:29] offset:0
	global_load_dword v94, v69, s[28:29] offset:-4096
	global_load_dword v95, v69, s[28:29] offset:0
	global_load_dword v97, v70, s[28:29] offset:-4096
	global_load_dword v98, v70, s[28:29] offset:0
	global_load_dword v99, v71, s[28:29] offset:-4096
	global_load_dword v100, v71, s[28:29] offset:0
	global_load_dword v101, v72, s[28:29] offset:-4096
	global_load_dword v102, v72, s[28:29] offset:0
	global_load_dword v103, v73, s[28:29] offset:-4096
	global_load_dword v104, v73, s[28:29] offset:0
	global_load_dword v105, v66, s[28:29] offset:-4032
	global_load_dword v106, v66, s[28:29] offset:64
	global_load_dword v107, v67, s[28:29] offset:-4032
	global_load_dword v108, v67, s[28:29] offset:64
	global_load_dword v109, v68, s[28:29] offset:-4032
	global_load_dword v110, v68, s[28:29] offset:64
	global_load_dword v111, v69, s[28:29] offset:-4032
	global_load_dword v112, v69, s[28:29] offset:64
	global_load_dword v116, v70, s[28:29] offset:-4032
	global_load_dword v117, v70, s[28:29] offset:64
	global_load_dword v118, v71, s[28:29] offset:-4032
	global_load_dword v119, v71, s[28:29] offset:64
	global_load_dword v120, v72, s[28:29] offset:-4032
	global_load_dword v121, v72, s[28:29] offset:64
	global_load_dword v122, v73, s[28:29] offset:-4032
	global_load_dword v123, v73, s[28:29] offset:64
	s_waitcnt vmcnt(32)
	v_add_f32_e32 v74, 1.0, v74
	v_add_f32_e32 v75, 1.0, v75
	v_add_f32_e32 v76, 1.0, v76
	v_add_f32_e32 v77, 1.0, v77
	s_waitcnt vmcnt(31)
	v_mul_f32_e32 v60, v60, v74
	v_fmac_f32_e32 v60, 0x3fb504f3, v78
	global_load_dword v78, v66, s[28:29] offset:-3968
	global_store_dword v66, v60, s[28:29] offset:-4096
	s_waitcnt vmcnt(32)
	v_mul_f32_e32 v61, v61, v74
	v_fmac_f32_e32 v61, 0x3fb504f3, v79
	global_load_dword v79, v66, s[28:29] offset:128
	global_store_dword v66, v61, s[28:29] offset:0
	s_waitcnt vmcnt(33)
	v_mul_f32_e32 v62, v62, v74
	v_fmac_f32_e32 v62, 0x3fb504f3, v82
	global_load_dword v82, v67, s[28:29] offset:-3968
	global_store_dword v67, v62, s[28:29] offset:-4096
	s_waitcnt vmcnt(34)
	v_mul_f32_e32 v63, v63, v74
	v_fmac_f32_e32 v63, 0x3fb504f3, v83
	global_load_dword v83, v67, s[28:29] offset:128
	global_store_dword v67, v63, s[28:29] offset:0
	s_waitcnt vmcnt(35)
	v_mul_f32_e32 v52, v52, v74
	v_fmac_f32_e32 v52, 0x3fb504f3, v91
	global_load_dword v91, v68, s[28:29] offset:-3968
	global_store_dword v68, v52, s[28:29] offset:-4096
	s_waitcnt vmcnt(36)
	v_mul_f32_e32 v53, v53, v74
	v_fmac_f32_e32 v53, 0x3fb504f3, v93
	global_load_dword v93, v68, s[28:29] offset:128
	global_store_dword v68, v53, s[28:29] offset:0
	s_waitcnt vmcnt(37)
	v_mul_f32_e32 v54, v54, v74
	v_fmac_f32_e32 v54, 0x3fb504f3, v94
	global_load_dword v94, v69, s[28:29] offset:-3968
	global_store_dword v69, v54, s[28:29] offset:-4096
	s_waitcnt vmcnt(38)
	v_mul_f32_e32 v55, v55, v74
	v_fmac_f32_e32 v55, 0x3fb504f3, v95
	global_load_dword v95, v69, s[28:29] offset:128
	global_store_dword v69, v55, s[28:29] offset:0
	s_waitcnt vmcnt(39)
	v_mul_f32_e32 v56, v56, v74
	v_fmac_f32_e32 v56, 0x3fb504f3, v97
	global_load_dword v97, v70, s[28:29] offset:-3968
	global_store_dword v70, v56, s[28:29] offset:-4096
	s_waitcnt vmcnt(40)
	v_mul_f32_e32 v57, v57, v74
	v_fmac_f32_e32 v57, 0x3fb504f3, v98
	global_load_dword v98, v70, s[28:29] offset:128
	global_store_dword v70, v57, s[28:29] offset:0
	s_waitcnt vmcnt(41)
	v_mul_f32_e32 v58, v58, v74
	v_fmac_f32_e32 v58, 0x3fb504f3, v99
	global_load_dword v99, v71, s[28:29] offset:-3968
	global_store_dword v71, v58, s[28:29] offset:-4096
	s_waitcnt vmcnt(42)
	v_mul_f32_e32 v59, v59, v74
	v_fmac_f32_e32 v59, 0x3fb504f3, v100
	global_load_dword v100, v71, s[28:29] offset:128
	global_store_dword v71, v59, s[28:29] offset:0
	s_waitcnt vmcnt(43)
	v_mul_f32_e32 v48, v48, v74
	v_fmac_f32_e32 v48, 0x3fb504f3, v101
	global_load_dword v101, v72, s[28:29] offset:-3968
	global_store_dword v72, v48, s[28:29] offset:-4096
	s_waitcnt vmcnt(44)
	v_mul_f32_e32 v49, v49, v74
	v_fmac_f32_e32 v49, 0x3fb504f3, v102
	global_load_dword v102, v72, s[28:29] offset:128
	global_store_dword v72, v49, s[28:29] offset:0
	s_waitcnt vmcnt(45)
	v_mul_f32_e32 v50, v50, v74
	v_fmac_f32_e32 v50, 0x3fb504f3, v103
	global_load_dword v103, v73, s[28:29] offset:-3968
	global_store_dword v73, v50, s[28:29] offset:-4096
	s_waitcnt vmcnt(46)
	v_mul_f32_e32 v51, v51, v74
	v_fmac_f32_e32 v51, 0x3fb504f3, v104
	global_load_dword v104, v73, s[28:29] offset:128
	global_store_dword v73, v51, s[28:29] offset:0
	s_waitcnt vmcnt(47)
	v_mul_f32_e32 v44, v44, v75
	v_fmac_f32_e32 v44, 0x3fb504f3, v105
	global_load_dword v105, v66, s[28:29] offset:-3904
	global_store_dword v66, v44, s[28:29] offset:-4032
	s_waitcnt vmcnt(48)
	v_mul_f32_e32 v45, v45, v75
	v_fmac_f32_e32 v45, 0x3fb504f3, v106
	global_load_dword v106, v66, s[28:29] offset:192
	global_store_dword v66, v45, s[28:29] offset:64
	s_waitcnt vmcnt(49)
	v_mul_f32_e32 v46, v46, v75
	v_fmac_f32_e32 v46, 0x3fb504f3, v107
	global_load_dword v107, v67, s[28:29] offset:-3904
	global_store_dword v67, v46, s[28:29] offset:-4032
	s_waitcnt vmcnt(50)
	v_mul_f32_e32 v47, v47, v75
	v_fmac_f32_e32 v47, 0x3fb504f3, v108
	global_load_dword v108, v67, s[28:29] offset:192
	global_store_dword v67, v47, s[28:29] offset:64
	s_waitcnt vmcnt(51)
	v_mul_f32_e32 v40, v40, v75
	v_fmac_f32_e32 v40, 0x3fb504f3, v109
	global_load_dword v109, v68, s[28:29] offset:-3904
	global_store_dword v68, v40, s[28:29] offset:-4032
	s_waitcnt vmcnt(52)
	v_mul_f32_e32 v41, v41, v75
	v_fmac_f32_e32 v41, 0x3fb504f3, v110
	global_load_dword v110, v68, s[28:29] offset:192
	global_store_dword v68, v41, s[28:29] offset:64
	s_waitcnt vmcnt(53)
	v_mul_f32_e32 v42, v42, v75
	v_fmac_f32_e32 v42, 0x3fb504f3, v111
	global_load_dword v111, v69, s[28:29] offset:-3904
	global_store_dword v69, v42, s[28:29] offset:-4032
	s_waitcnt vmcnt(54)
	v_mul_f32_e32 v43, v43, v75
	v_fmac_f32_e32 v43, 0x3fb504f3, v112
	global_load_dword v112, v69, s[28:29] offset:192
	global_store_dword v69, v43, s[28:29] offset:64
	s_waitcnt vmcnt(55)
	v_mul_f32_e32 v36, v36, v75
	v_fmac_f32_e32 v36, 0x3fb504f3, v116
	global_load_dword v116, v70, s[28:29] offset:-3904
	global_store_dword v70, v36, s[28:29] offset:-4032
	s_waitcnt vmcnt(56)
	v_mul_f32_e32 v37, v37, v75
	v_fmac_f32_e32 v37, 0x3fb504f3, v117
	global_load_dword v117, v70, s[28:29] offset:192
	global_store_dword v70, v37, s[28:29] offset:64
	s_waitcnt vmcnt(57)
	v_mul_f32_e32 v38, v38, v75
	v_fmac_f32_e32 v38, 0x3fb504f3, v118
	global_load_dword v118, v71, s[28:29] offset:-3904
	global_store_dword v71, v38, s[28:29] offset:-4032
	s_waitcnt vmcnt(58)
	v_mul_f32_e32 v39, v39, v75
	v_fmac_f32_e32 v39, 0x3fb504f3, v119
	global_load_dword v119, v71, s[28:29] offset:192
	global_store_dword v71, v39, s[28:29] offset:64
	s_waitcnt vmcnt(59)
	v_mul_f32_e32 v32, v32, v75
	v_fmac_f32_e32 v32, 0x3fb504f3, v120
	global_load_dword v120, v72, s[28:29] offset:-3904
	global_store_dword v72, v32, s[28:29] offset:-4032
	s_waitcnt vmcnt(60)
	v_mul_f32_e32 v33, v33, v75
	v_fmac_f32_e32 v33, 0x3fb504f3, v121
	global_load_dword v121, v72, s[28:29] offset:192
	global_store_dword v72, v33, s[28:29] offset:64
	s_waitcnt vmcnt(61)
	v_mul_f32_e32 v34, v34, v75
	v_fmac_f32_e32 v34, 0x3fb504f3, v122
	global_load_dword v122, v73, s[28:29] offset:-3904
	global_store_dword v73, v34, s[28:29] offset:-4032
	s_waitcnt vmcnt(62)
	v_mul_f32_e32 v35, v35, v75
	v_fmac_f32_e32 v35, 0x3fb504f3, v123
	global_load_dword v123, v73, s[28:29] offset:192
	global_store_dword v73, v35, s[28:29] offset:64
	s_waitcnt vmcnt(63)
	v_mul_f32_e32 v28, v28, v76
	v_fmac_f32_e32 v28, 0x3fb504f3, v78
	global_store_dword v66, v28, s[28:29] offset:-3968
	s_waitcnt vmcnt(62)
	v_mul_f32_e32 v29, v29, v76
	v_fmac_f32_e32 v29, 0x3fb504f3, v79
	global_store_dword v66, v29, s[28:29] offset:128
	s_waitcnt vmcnt(61)
	v_mul_f32_e32 v30, v30, v76
	v_fmac_f32_e32 v30, 0x3fb504f3, v82
	global_store_dword v67, v30, s[28:29] offset:-3968
	s_waitcnt vmcnt(60)
	v_mul_f32_e32 v31, v31, v76
	v_fmac_f32_e32 v31, 0x3fb504f3, v83
	global_store_dword v67, v31, s[28:29] offset:128
	s_waitcnt vmcnt(59)
	v_mul_f32_e32 v24, v24, v76
	v_fmac_f32_e32 v24, 0x3fb504f3, v91
	global_store_dword v68, v24, s[28:29] offset:-3968
	s_waitcnt vmcnt(58)
	v_mul_f32_e32 v25, v25, v76
	v_fmac_f32_e32 v25, 0x3fb504f3, v93
	global_store_dword v68, v25, s[28:29] offset:128
	s_waitcnt vmcnt(57)
	v_mul_f32_e32 v26, v26, v76
	v_fmac_f32_e32 v26, 0x3fb504f3, v94
	global_store_dword v69, v26, s[28:29] offset:-3968
	s_waitcnt vmcnt(56)
	v_mul_f32_e32 v27, v27, v76
	v_fmac_f32_e32 v27, 0x3fb504f3, v95
	global_store_dword v69, v27, s[28:29] offset:128
	s_waitcnt vmcnt(55)
	v_mul_f32_e32 v20, v20, v76
	v_fmac_f32_e32 v20, 0x3fb504f3, v97
	global_store_dword v70, v20, s[28:29] offset:-3968
	s_waitcnt vmcnt(54)
	v_mul_f32_e32 v21, v21, v76
	v_fmac_f32_e32 v21, 0x3fb504f3, v98
	global_store_dword v70, v21, s[28:29] offset:128
	s_waitcnt vmcnt(53)
	v_mul_f32_e32 v22, v22, v76
	v_fmac_f32_e32 v22, 0x3fb504f3, v99
	global_store_dword v71, v22, s[28:29] offset:-3968
	s_waitcnt vmcnt(52)
	v_mul_f32_e32 v23, v23, v76
	v_fmac_f32_e32 v23, 0x3fb504f3, v100
	global_store_dword v71, v23, s[28:29] offset:128
	s_waitcnt vmcnt(51)
	v_mul_f32_e32 v16, v16, v76
	v_fmac_f32_e32 v16, 0x3fb504f3, v101
	global_store_dword v72, v16, s[28:29] offset:-3968
	s_waitcnt vmcnt(50)
	v_mul_f32_e32 v17, v17, v76
	v_fmac_f32_e32 v17, 0x3fb504f3, v102
	global_store_dword v72, v17, s[28:29] offset:128
	s_waitcnt vmcnt(49)
	v_mul_f32_e32 v18, v18, v76
	v_fmac_f32_e32 v18, 0x3fb504f3, v103
	global_store_dword v73, v18, s[28:29] offset:-3968
	s_waitcnt vmcnt(48)
	v_mul_f32_e32 v19, v19, v76
	v_fmac_f32_e32 v19, 0x3fb504f3, v104
	global_store_dword v73, v19, s[28:29] offset:128
	s_waitcnt vmcnt(47)
	v_mul_f32_e32 v12, v12, v77
	v_fmac_f32_e32 v12, 0x3fb504f3, v105
	global_store_dword v66, v12, s[28:29] offset:-3904
	s_waitcnt vmcnt(46)
	v_mul_f32_e32 v13, v13, v77
	v_fmac_f32_e32 v13, 0x3fb504f3, v106
	global_store_dword v66, v13, s[28:29] offset:192
	s_waitcnt vmcnt(45)
	v_mul_f32_e32 v14, v14, v77
	v_fmac_f32_e32 v14, 0x3fb504f3, v107
	global_store_dword v67, v14, s[28:29] offset:-3904
	s_waitcnt vmcnt(44)
	v_mul_f32_e32 v15, v15, v77
	v_fmac_f32_e32 v15, 0x3fb504f3, v108
	global_store_dword v67, v15, s[28:29] offset:192
	s_waitcnt vmcnt(43)
	v_mul_f32_e32 v8, v8, v77
	v_fmac_f32_e32 v8, 0x3fb504f3, v109
	global_store_dword v68, v8, s[28:29] offset:-3904
	s_waitcnt vmcnt(42)
	v_mul_f32_e32 v9, v9, v77
	v_fmac_f32_e32 v9, 0x3fb504f3, v110
	global_store_dword v68, v9, s[28:29] offset:192
	s_waitcnt vmcnt(41)
	v_mul_f32_e32 v10, v10, v77
	v_fmac_f32_e32 v10, 0x3fb504f3, v111
	global_store_dword v69, v10, s[28:29] offset:-3904
	s_waitcnt vmcnt(40)
	v_mul_f32_e32 v11, v11, v77
	v_fmac_f32_e32 v11, 0x3fb504f3, v112
	global_store_dword v69, v11, s[28:29] offset:192
	s_waitcnt vmcnt(39)
	v_mul_f32_e32 v4, v4, v77
	v_fmac_f32_e32 v4, 0x3fb504f3, v116
	global_store_dword v70, v4, s[28:29] offset:-3904
	s_waitcnt vmcnt(38)
	v_mul_f32_e32 v5, v5, v77
	v_fmac_f32_e32 v5, 0x3fb504f3, v117
	global_store_dword v70, v5, s[28:29] offset:192
	s_waitcnt vmcnt(37)
	v_mul_f32_e32 v6, v6, v77
	v_fmac_f32_e32 v6, 0x3fb504f3, v118
	global_store_dword v71, v6, s[28:29] offset:-3904
	s_waitcnt vmcnt(36)
	v_mul_f32_e32 v7, v7, v77
	v_fmac_f32_e32 v7, 0x3fb504f3, v119
	global_store_dword v71, v7, s[28:29] offset:192
	s_waitcnt vmcnt(35)
	v_mul_f32_e32 v0, v0, v77
	v_fmac_f32_e32 v0, 0x3fb504f3, v120
	global_store_dword v72, v0, s[28:29] offset:-3904
	s_waitcnt vmcnt(34)
	v_mul_f32_e32 v1, v1, v77
	v_fmac_f32_e32 v1, 0x3fb504f3, v121
	global_store_dword v72, v1, s[28:29] offset:192
	s_waitcnt vmcnt(33)
	v_mul_f32_e32 v2, v2, v77
	v_fmac_f32_e32 v2, 0x3fb504f3, v122
	global_store_dword v73, v2, s[28:29] offset:-3904
	s_waitcnt vmcnt(32)
	v_mul_f32_e32 v3, v3, v77
	v_fmac_f32_e32 v3, 0x3fb504f3, v123
	global_store_dword v73, v3, s[28:29] offset:192
	s_cbranch_scc0 .LBB0_600

.LBB0_650:
	s_add_i32 s4, s13, 0xffff8000
	v_mov_b32_e32 v64, v182
	s_waitcnt vmcnt(0)
	s_waitcnt vmcnt(0) lgkmcnt(0)
	s_barrier
	s_and_b32 s14, s13, 0x8000
	s_and_b32 s15, s4, 0x8000
	v_or_b32_e32 v71, s15, v86
	v_lshrrev_b32_e32 v65, 4, v64
	v_ashrrev_i32_e32 v66, 3, v64
	v_add_u32_e32 v68, 0x100, v64
	v_lshl_add_u32 v67, v64, 4, s14
	v_add_u32_e32 v69, 0x200, v64
	v_add_u32_e32 v72, s0, v66
	v_bitop3_b32 v73, v65, 7, v64 bitop3:0x48
	v_ashrrev_i32_e32 v74, 3, v68
	s_add_u32 s8, s30, s2
	v_add_u32_e32 v70, 0x300, v64
	v_lshl_add_u32 v68, v68, 4, s14
	v_ashrrev_i32_e32 v75, 3, v69
	v_lshl_add_u32 v69, v69, 4, s14
	v_add_u32_e32 v77, 0x4000, v67
	v_add3_u32 v91, v71, v87, v88
	v_add3_u32 v80, v71, v89, v88
	v_mad_i64_i32 v[64:65], s[4:5], v72, s64, 0
	v_lshlrev_b32_e32 v81, 4, v73
	v_add_u32_e32 v71, s0, v74
	s_addc_u32 s9, s31, s3
	v_ashrrev_i32_e32 v76, 3, v70
	v_lshl_add_u32 v70, v70, 4, s14
	v_readfirstlane_b32 s17, v68
	v_add_u32_e32 v72, s0, v75
	v_readfirstlane_b32 s18, v69
	v_readfirstlane_b32 s20, v77
	v_add_u32_e32 v77, 0x4000, v68
	v_add_u32_e32 v79, 0x4000, v69
	v_or_b32_e32 v64, v64, v81
	v_mad_i64_i32 v[68:69], s[4:5], v71, s64, 0
	v_readfirstlane_b32 s16, v67
	v_add_u32_e32 v73, s0, v76
	v_readfirstlane_b32 s19, v70
	v_add_u32_e32 v83, 0x4000, v70
	v_mad_i64_i32 v[70:71], s[4:5], v72, s64, 0
	v_lshl_add_u64 v[64:65], s[8:9], 0, v[64:65]
	v_or_b32_e32 v68, v68, v81
	v_add_u32_e32 v66, s12, v66
	v_mad_i64_i32 v[72:73], s[4:5], v73, s64, 0
	v_or_b32_e32 v70, v70, v81
	v_lshl_add_u64 v[64:65], v[64:65], 0, s[88:89]
	v_lshl_add_u64 v[68:69], s[8:9], 0, v[68:69]
	s_mov_b32 m0, s16
	v_mad_i64_i32 v[66:67], s[4:5], v66, s64, 0
	v_add_u32_e32 v74, s12, v74
	v_or_b32_e32 v72, v72, v81
	v_lshl_add_u64 v[70:71], s[8:9], 0, v[70:71]
	global_load_lds_dwordx4 v[64:65], off
	v_lshl_add_u64 v[64:65], v[68:69], 0, s[88:89]
	s_mov_b32 m0, s17
	v_add_u32_e32 v78, s12, v75
	v_or_b32_e32 v66, v66, v81
	v_mad_i64_i32 v[74:75], s[4:5], v74, s64, 0
	v_lshl_add_u64 v[72:73], s[8:9], 0, v[72:73]
	v_lshl_add_u64 v[68:69], v[70:71], 0, s[88:89]
	global_load_lds_dwordx4 v[64:65], off
	s_mov_b32 m0, s18
	v_add_u32_e32 v82, s12, v76
	v_readfirstlane_b32 s21, v77
	v_mad_i64_i32 v[76:77], s[4:5], v78, s64, 0
	v_lshl_add_u64 v[66:67], s[8:9], 0, v[66:67]
	v_or_b32_e32 v74, v74, v81
	v_lshl_add_u64 v[70:71], v[72:73], 0, s[88:89]
	global_load_lds_dwordx4 v[68:69], off
	s_mov_b32 m0, s19
	v_readfirstlane_b32 s22, v79
	v_mad_i64_i32 v[78:79], s[4:5], v82, s64, 0
	v_or_b32_e32 v76, v76, v81
	v_lshl_add_u64 v[66:67], v[66:67], 0, s[6:7]
	v_lshl_add_u64 v[74:75], s[8:9], 0, v[74:75]
	global_load_lds_dwordx4 v[70:71], off
	s_mov_b32 m0, s20
	v_or_b32_e32 v78, v78, v81
	v_lshl_add_u64 v[76:77], s[8:9], 0, v[76:77]
	v_lshl_add_u64 v[72:73], v[74:75], 0, s[6:7]
	global_load_lds_dwordx4 v[66:67], off
	s_mov_b32 m0, s21
	v_readfirstlane_b32 s4, v83
	v_lshl_add_u64 v[78:79], s[8:9], 0, v[78:79]
	v_lshl_add_u64 v[74:75], v[76:77], 0, s[6:7]
	global_load_lds_dwordx4 v[72:73], off
	s_mov_b32 m0, s22
	v_lshl_add_u64 v[76:77], v[78:79], 0, s[6:7]
	global_load_lds_dwordx4 v[74:75], off
	s_mov_b32 m0, s4
	s_add_u32 s2, s2, 0x80
	global_load_lds_dwordx4 v[76:77], off
	ds_read_b128 v[64:67], v91
	ds_read_b128 v[68:71], v80 offset:16384
	ds_read_b128 v[72:75], v80 offset:18432
	ds_read_b128 v[76:79], v80 offset:20480
	ds_read_b128 v[80:83], v80 offset:22528
	s_waitcnt lgkmcnt(0)
	v_mfma_f32_16x16x32_f16 v[60:63], v[64:67], v[68:71], v[60:63]
	s_addc_u32 s3, s3, 0
	s_add_i32 s13, s13, 0x8000
	s_cmpk_eq_i32 s2, 0x1580
	v_mfma_f32_16x16x32_f16 v[56:59], v[64:67], v[72:75], v[56:59]
	v_mfma_f32_16x16x32_f16 v[52:55], v[64:67], v[76:79], v[52:55]
	v_mfma_f32_16x16x32_f16 v[48:51], v[64:67], v[80:83], v[48:51]
	ds_read_b128 v[64:67], v91 offset:2048
	s_waitcnt lgkmcnt(0)
	v_mfma_f32_16x16x32_f16 v[44:47], v[64:67], v[68:71], v[44:47]
	v_mfma_f32_16x16x32_f16 v[40:43], v[64:67], v[72:75], v[40:43]
	v_mfma_f32_16x16x32_f16 v[36:39], v[64:67], v[76:79], v[36:39]
	v_mfma_f32_16x16x32_f16 v[32:35], v[64:67], v[80:83], v[32:35]
	ds_read_b128 v[64:67], v91 offset:4096
	s_waitcnt lgkmcnt(0)
	v_mfma_f32_16x16x32_f16 v[24:27], v[64:67], v[68:71], v[24:27]
	v_mfma_f32_16x16x32_f16 v[20:23], v[64:67], v[72:75], v[20:23]
	v_mfma_f32_16x16x32_f16 v[16:19], v[64:67], v[76:79], v[16:19]
	v_mfma_f32_16x16x32_f16 v[12:15], v[64:67], v[80:83], v[12:15]
	ds_read_b128 v[64:67], v91 offset:6144
	s_waitcnt lgkmcnt(0)
	v_mfma_f32_16x16x32_f16 v[8:11], v[64:67], v[68:71], v[8:11]
	v_or_b32_e32 v68, s15, v90
	v_add3_u32 v91, v68, v87, v88
	v_add3_u32 v92, v68, v89, v88
	ds_read_b128 v[68:71], v91
	v_mfma_f32_16x16x32_f16 v[4:7], v[64:67], v[72:75], v[4:7]
	ds_read_b128 v[72:75], v92 offset:18432
	v_mfma_f32_16x16x32_f16 v[0:3], v[64:67], v[76:79], v[0:3]
	ds_read_b128 v[76:79], v92 offset:20480
	v_mfma_f32_16x16x32_f16 v[28:31], v[64:67], v[80:83], v[28:31]
	ds_read_b128 v[64:67], v92 offset:16384
	ds_read_b128 v[80:83], v92 offset:22528
	s_waitcnt lgkmcnt(1)
	v_mfma_f32_16x16x32_f16 v[60:63], v[68:71], v[64:67], v[60:63]
	v_mfma_f32_16x16x32_f16 v[56:59], v[68:71], v[72:75], v[56:59]
	v_mfma_f32_16x16x32_f16 v[52:55], v[68:71], v[76:79], v[52:55]
	s_waitcnt lgkmcnt(0)
	v_mfma_f32_16x16x32_f16 v[48:51], v[68:71], v[80:83], v[48:51]
	ds_read_b128 v[68:71], v91 offset:2048
	s_waitcnt lgkmcnt(0)
	v_mfma_f32_16x16x32_f16 v[44:47], v[68:71], v[64:67], v[44:47]
	v_mfma_f32_16x16x32_f16 v[40:43], v[68:71], v[72:75], v[40:43]
	v_mfma_f32_16x16x32_f16 v[36:39], v[68:71], v[76:79], v[36:39]
	v_mfma_f32_16x16x32_f16 v[32:35], v[68:71], v[80:83], v[32:35]
	ds_read_b128 v[68:71], v91 offset:4096
	s_waitcnt lgkmcnt(0)
	v_mfma_f32_16x16x32_f16 v[24:27], v[68:71], v[64:67], v[24:27]
	v_mfma_f32_16x16x32_f16 v[20:23], v[68:71], v[72:75], v[20:23]
	v_mfma_f32_16x16x32_f16 v[16:19], v[68:71], v[76:79], v[16:19]
	v_mfma_f32_16x16x32_f16 v[12:15], v[68:71], v[80:83], v[12:15]
	ds_read_b128 v[68:71], v91 offset:6144
	s_waitcnt lgkmcnt(0)
	v_mfma_f32_16x16x32_f16 v[8:11], v[68:71], v[64:67], v[8:11]
	v_mfma_f32_16x16x32_f16 v[4:7], v[68:71], v[72:75], v[4:7]
	v_mfma_f32_16x16x32_f16 v[0:3], v[68:71], v[76:79], v[0:3]
	v_mfma_f32_16x16x32_f16 v[28:31], v[68:71], v[80:83], v[28:31]
	s_cbranch_scc0 .LBB0_650
	v_add_u32_e32 v80, s14, v86
	v_add3_u32 v76, v80, v87, v88
	v_add3_u32 v91, v80, v89, v88
	s_waitcnt vmcnt(0)
	s_barrier
	ds_read_b128 v[64:67], v76
	ds_read_b128 v[68:71], v76 offset:2048
	ds_read_b128 v[72:75], v76 offset:4096
	ds_read_b128 v[76:79], v76 offset:6144
	ds_read_b128 v[80:83], v91 offset:16384
	ds_read_b128 v[92:95], v91 offset:18432
	ds_read_b128 v[96:99], v91 offset:20480
	ds_read_b128 v[100:103], v91 offset:22528
	s_waitcnt lgkmcnt(3)
	v_mfma_f32_16x16x32_f16 v[60:63], v[64:67], v[80:83], v[60:63]
	s_ashr_i32 s2, s0, 31
	s_lshr_b32 s2, s2, 19
	s_add_i32 s2, s0, s2
	s_waitcnt lgkmcnt(2)
	v_mfma_f32_16x16x32_f16 v[56:59], v[64:67], v[92:95], v[56:59]
	s_ashr_i32 s2, s2, 13
	s_add_i32 s2, s2, s10
	s_mul_hi_i32 s3, s2, 0x9000
	s_waitcnt lgkmcnt(1)
	v_mfma_f32_16x16x32_f16 v[52:55], v[64:67], v[96:99], v[52:55]
	s_mul_i32 s2, s2, 0x9000
	s_add_u32 s2, s50, s2
	s_addc_u32 s3, s51, s3
	s_waitcnt lgkmcnt(0)
	v_mfma_f32_16x16x32_f16 v[48:51], v[64:67], v[100:103], v[48:51]
	s_add_i32 s11, s11, s59
	s_cmpk_gt_i32 s11, 0x7ff
	v_mfma_f32_16x16x32_f16 v[64:67], v[68:71], v[80:83], v[44:47]
	v_mfma_f32_16x16x32_f16 v[40:43], v[68:71], v[92:95], v[40:43]
	v_mfma_f32_16x16x32_f16 v[36:39], v[68:71], v[96:99], v[36:39]
	v_mfma_f32_16x16x32_f16 v[32:35], v[68:71], v[100:103], v[32:35]
	v_mfma_f32_16x16x32_f16 v[68:71], v[72:75], v[80:83], v[24:27]
	v_mfma_f32_16x16x32_f16 v[20:23], v[72:75], v[92:95], v[20:23]
	v_mfma_f32_16x16x32_f16 v[16:19], v[72:75], v[96:99], v[16:19]
	v_mfma_f32_16x16x32_f16 v[72:75], v[72:75], v[100:103], v[12:15]
	s_nop 2
	v_add_u32_e32 v12, s14, v90
	v_add3_u32 v13, v12, v87, v88
	v_add3_u32 v12, v12, v89, v88
	v_mfma_f32_16x16x32_f16 v[80:83], v[76:79], v[80:83], v[8:11]
	v_mfma_f32_16x16x32_f16 v[92:95], v[76:79], v[92:95], v[4:7]
	v_mfma_f32_16x16x32_f16 v[0:3], v[76:79], v[96:99], v[0:3]
	v_mfma_f32_16x16x32_f16 v[76:79], v[76:79], v[100:103], v[28:31]
	s_nop 0
	ds_read_b128 v[4:7], v13
	ds_read_b128 v[8:11], v13 offset:2048
	ds_read_b128 v[96:99], v13 offset:4096
	ds_read_b128 v[100:103], v13 offset:6144
	ds_read_b128 v[104:107], v12 offset:16384
	ds_read_b128 v[108:111], v12 offset:18432
	ds_read_b128 v[116:119], v12 offset:20480
	ds_read_b128 v[120:123], v12 offset:22528
	s_waitcnt lgkmcnt(1)
	v_mfma_f32_16x16x32_f16 v[28:31], v[4:7], v[116:119], v[52:55]
	v_mfma_f32_16x16x32_f16 v[52:55], v[8:11], v[104:107], v[64:67]
	s_nop 2
	v_or_b32_e32 v64, s12, v84
	v_ashrrev_i32_e32 v65, 31, v64
	v_mfma_f32_16x16x32_f16 v[60:63], v[4:7], v[104:107], v[60:63]
	v_mfma_f32_16x16x32_f16 v[44:47], v[4:7], v[108:111], v[56:59]
	s_waitcnt lgkmcnt(0)
	v_mfma_f32_16x16x32_f16 v[12:15], v[4:7], v[120:123], v[48:51]
	v_mfma_f32_16x16x32_f16 v[24:27], v[8:11], v[116:119], v[36:39]
	v_mfma_f32_16x16x32_f16 v[56:59], v[96:99], v[104:107], v[68:71]
	v_mfma_f32_16x16x32_f16 v[36:39], v[96:99], v[108:111], v[20:23]
	v_mfma_f32_16x16x32_f16 v[20:23], v[96:99], v[116:119], v[16:19]
	v_mfma_f32_16x16x32_f16 v[4:7], v[96:99], v[120:123], v[72:75]
	v_lshlrev_b64 v[96:97], 2, v[64:65]
	v_lshl_add_u64 v[64:65], s[2:3], 0, v[96:97]
	v_mfma_f32_16x16x32_f16 v[40:43], v[8:11], v[108:111], v[40:43]
	v_mfma_f32_16x16x32_f16 v[8:11], v[8:11], v[120:123], v[32:35]
	v_mfma_f32_16x16x32_f16 v[32:35], v[100:103], v[108:111], v[92:95]
	s_nop 2
	v_add_u32_e32 v92, s0, v85
	s_mov_b32 s0, 0x8000
	v_mfma_f32_16x16x32_f16 v[48:51], v[100:103], v[104:107], v[80:83]
	v_ashrrev_i32_e32 v93, 31, v92
	v_or_b32_e32 v94, 48, v92
	v_ashrrev_i32_e32 v95, 31, v94
	v_add_co_u32_e32 v80, vcc, s0, v64
	v_mfma_f32_16x16x32_f16 v[16:19], v[100:103], v[116:119], v[0:3]
	s_nop 0
	v_addc_co_u32_e32 v81, vcc, 0, v65, vcc
	global_load_dword v64, v[80:81], off
	v_mfma_f32_16x16x32_f16 v[0:3], v[100:103], v[120:123], v[76:79]
	v_lshl_add_u32 v65, v92, 12, v96
	v_add_u32_e32 v66, 0x1000, v65
	v_add_u32_e32 v67, 0x3000, v65
	v_add_u32_e32 v68, 0x11000, v65
	v_add_u32_e32 v69, 0x13000, v65
	v_add_u32_e32 v70, 0x21000, v65
	v_add_u32_e32 v71, 0x23000, v65
	v_add_u32_e32 v72, 0x31000, v65
	v_add_u32_e32 v73, 0x33000, v65
	global_load_dword v74, v[80:81], off offset:0
	global_load_dword v75, v[80:81], off offset:64
	global_load_dword v76, v[80:81], off offset:128
	global_load_dword v77, v[80:81], off offset:192
	global_load_dword v78, v66, s[28:29] offset:-4096
	global_load_dword v79, v66, s[28:29] offset:0
	global_load_dword v82, v67, s[28:29] offset:-4096
	global_load_dword v83, v67, s[28:29] offset:0
	global_load_dword v91, v68, s[28:29] offset:-4096
	global_load_dword v93, v68, s[28:29] offset:0
	global_load_dword v94, v69, s[28:29] offset:-4096
	global_load_dword v95, v69, s[28:29] offset:0
	global_load_dword v97, v70, s[28:29] offset:-4096
	global_load_dword v98, v70, s[28:29] offset:0
	global_load_dword v99, v71, s[28:29] offset:-4096
	global_load_dword v100, v71, s[28:29] offset:0
	global_load_dword v101, v72, s[28:29] offset:-4096
	global_load_dword v102, v72, s[28:29] offset:0
	global_load_dword v103, v73, s[28:29] offset:-4096
	global_load_dword v104, v73, s[28:29] offset:0
	global_load_dword v105, v66, s[28:29] offset:-4032
	global_load_dword v106, v66, s[28:29] offset:64
	global_load_dword v107, v67, s[28:29] offset:-4032
	global_load_dword v108, v67, s[28:29] offset:64
	global_load_dword v109, v68, s[28:29] offset:-4032
	global_load_dword v110, v68, s[28:29] offset:64
	global_load_dword v111, v69, s[28:29] offset:-4032
	global_load_dword v112, v69, s[28:29] offset:64
	global_load_dword v116, v70, s[28:29] offset:-4032
	global_load_dword v117, v70, s[28:29] offset:64
	global_load_dword v118, v71, s[28:29] offset:-4032
	global_load_dword v119, v71, s[28:29] offset:64
	global_load_dword v120, v72, s[28:29] offset:-4032
	global_load_dword v121, v72, s[28:29] offset:64
	global_load_dword v122, v73, s[28:29] offset:-4032
	global_load_dword v123, v73, s[28:29] offset:64
	s_waitcnt vmcnt(32)
	v_add_f32_e32 v74, 1.0, v74
	v_add_f32_e32 v75, 1.0, v75
	v_add_f32_e32 v76, 1.0, v76
	v_add_f32_e32 v77, 1.0, v77
	v_mul_f32_e32 v74, 0.5, v74
	v_mul_f32_e32 v75, 0.5, v75
	v_mul_f32_e32 v76, 0.5, v76
	v_mul_f32_e32 v77, 0.5, v77
	s_waitcnt vmcnt(31)
	v_mul_f32_e32 v60, v60, v74
	v_fmac_f32_e32 v60, 0x3fb504f3, v78
	global_load_dword v78, v66, s[28:29] offset:-3968
	global_store_dword v66, v60, s[28:29] offset:-4096
	s_waitcnt vmcnt(32)
	v_mul_f32_e32 v61, v61, v74
	v_fmac_f32_e32 v61, 0x3fb504f3, v79
	global_load_dword v79, v66, s[28:29] offset:128
	global_store_dword v66, v61, s[28:29] offset:0
	s_waitcnt vmcnt(33)
	v_mul_f32_e32 v62, v62, v74
	v_fmac_f32_e32 v62, 0x3fb504f3, v82
	global_load_dword v82, v67, s[28:29] offset:-3968
	global_store_dword v67, v62, s[28:29] offset:-4096
	s_waitcnt vmcnt(34)
	v_mul_f32_e32 v63, v63, v74
	v_fmac_f32_e32 v63, 0x3fb504f3, v83
	global_load_dword v83, v67, s[28:29] offset:128
	global_store_dword v67, v63, s[28:29] offset:0
	s_waitcnt vmcnt(35)
	v_mul_f32_e32 v52, v52, v74
	v_fmac_f32_e32 v52, 0x3fb504f3, v91
	global_load_dword v91, v68, s[28:29] offset:-3968
	global_store_dword v68, v52, s[28:29] offset:-4096
	s_waitcnt vmcnt(36)
	v_mul_f32_e32 v53, v53, v74
	v_fmac_f32_e32 v53, 0x3fb504f3, v93
	global_load_dword v93, v68, s[28:29] offset:128
	global_store_dword v68, v53, s[28:29] offset:0
	s_waitcnt vmcnt(37)
	v_mul_f32_e32 v54, v54, v74
	v_fmac_f32_e32 v54, 0x3fb504f3, v94
	global_load_dword v94, v69, s[28:29] offset:-3968
	global_store_dword v69, v54, s[28:29] offset:-4096
	s_waitcnt vmcnt(38)
	v_mul_f32_e32 v55, v55, v74
	v_fmac_f32_e32 v55, 0x3fb504f3, v95
	global_load_dword v95, v69, s[28:29] offset:128
	global_store_dword v69, v55, s[28:29] offset:0
	s_waitcnt vmcnt(39)
	v_mul_f32_e32 v56, v56, v74
	v_fmac_f32_e32 v56, 0x3fb504f3, v97
	global_load_dword v97, v70, s[28:29] offset:-3968
	global_store_dword v70, v56, s[28:29] offset:-4096
	s_waitcnt vmcnt(40)
	v_mul_f32_e32 v57, v57, v74
	v_fmac_f32_e32 v57, 0x3fb504f3, v98
	global_load_dword v98, v70, s[28:29] offset:128
	global_store_dword v70, v57, s[28:29] offset:0
	s_waitcnt vmcnt(41)
	v_mul_f32_e32 v58, v58, v74
	v_fmac_f32_e32 v58, 0x3fb504f3, v99
	global_load_dword v99, v71, s[28:29] offset:-3968
	global_store_dword v71, v58, s[28:29] offset:-4096
	s_waitcnt vmcnt(42)
	v_mul_f32_e32 v59, v59, v74
	v_fmac_f32_e32 v59, 0x3fb504f3, v100
	global_load_dword v100, v71, s[28:29] offset:128
	global_store_dword v71, v59, s[28:29] offset:0
	s_waitcnt vmcnt(43)
	v_mul_f32_e32 v48, v48, v74
	v_fmac_f32_e32 v48, 0x3fb504f3, v101
	global_load_dword v101, v72, s[28:29] offset:-3968
	global_store_dword v72, v48, s[28:29] offset:-4096
	s_waitcnt vmcnt(44)
	v_mul_f32_e32 v49, v49, v74
	v_fmac_f32_e32 v49, 0x3fb504f3, v102
	global_load_dword v102, v72, s[28:29] offset:128
	global_store_dword v72, v49, s[28:29] offset:0
	s_waitcnt vmcnt(45)
	v_mul_f32_e32 v50, v50, v74
	v_fmac_f32_e32 v50, 0x3fb504f3, v103
	global_load_dword v103, v73, s[28:29] offset:-3968
	global_store_dword v73, v50, s[28:29] offset:-4096
	s_waitcnt vmcnt(46)
	v_mul_f32_e32 v51, v51, v74
	v_fmac_f32_e32 v51, 0x3fb504f3, v104
	global_load_dword v104, v73, s[28:29] offset:128
	global_store_dword v73, v51, s[28:29] offset:0
	s_waitcnt vmcnt(47)
	v_mul_f32_e32 v44, v44, v75
	v_fmac_f32_e32 v44, 0x3fb504f3, v105
	global_load_dword v105, v66, s[28:29] offset:-3904
	global_store_dword v66, v44, s[28:29] offset:-4032
	s_waitcnt vmcnt(48)
	v_mul_f32_e32 v45, v45, v75
	v_fmac_f32_e32 v45, 0x3fb504f3, v106
	global_load_dword v106, v66, s[28:29] offset:192
	global_store_dword v66, v45, s[28:29] offset:64
	s_waitcnt vmcnt(49)
	v_mul_f32_e32 v46, v46, v75
	v_fmac_f32_e32 v46, 0x3fb504f3, v107
	global_load_dword v107, v67, s[28:29] offset:-3904
	global_store_dword v67, v46, s[28:29] offset:-4032
	s_waitcnt vmcnt(50)
	v_mul_f32_e32 v47, v47, v75
	v_fmac_f32_e32 v47, 0x3fb504f3, v108
	global_load_dword v108, v67, s[28:29] offset:192
	global_store_dword v67, v47, s[28:29] offset:64
	s_waitcnt vmcnt(51)
	v_mul_f32_e32 v40, v40, v75
	v_fmac_f32_e32 v40, 0x3fb504f3, v109
	global_load_dword v109, v68, s[28:29] offset:-3904
	global_store_dword v68, v40, s[28:29] offset:-4032
	s_waitcnt vmcnt(52)
	v_mul_f32_e32 v41, v41, v75
	v_fmac_f32_e32 v41, 0x3fb504f3, v110
	global_load_dword v110, v68, s[28:29] offset:192
	global_store_dword v68, v41, s[28:29] offset:64
	s_waitcnt vmcnt(53)
	v_mul_f32_e32 v42, v42, v75
	v_fmac_f32_e32 v42, 0x3fb504f3, v111
	global_load_dword v111, v69, s[28:29] offset:-3904
	global_store_dword v69, v42, s[28:29] offset:-4032
	s_waitcnt vmcnt(54)
	v_mul_f32_e32 v43, v43, v75
	v_fmac_f32_e32 v43, 0x3fb504f3, v112
	global_load_dword v112, v69, s[28:29] offset:192
	global_store_dword v69, v43, s[28:29] offset:64
	s_waitcnt vmcnt(55)
	v_mul_f32_e32 v36, v36, v75
	v_fmac_f32_e32 v36, 0x3fb504f3, v116
	global_load_dword v116, v70, s[28:29] offset:-3904
	global_store_dword v70, v36, s[28:29] offset:-4032
	s_waitcnt vmcnt(56)
	v_mul_f32_e32 v37, v37, v75
	v_fmac_f32_e32 v37, 0x3fb504f3, v117
	global_load_dword v117, v70, s[28:29] offset:192
	global_store_dword v70, v37, s[28:29] offset:64
	s_waitcnt vmcnt(57)
	v_mul_f32_e32 v38, v38, v75
	v_fmac_f32_e32 v38, 0x3fb504f3, v118
	global_load_dword v118, v71, s[28:29] offset:-3904
	global_store_dword v71, v38, s[28:29] offset:-4032
	s_waitcnt vmcnt(58)
	v_mul_f32_e32 v39, v39, v75
	v_fmac_f32_e32 v39, 0x3fb504f3, v119
	global_load_dword v119, v71, s[28:29] offset:192
	global_store_dword v71, v39, s[28:29] offset:64
	s_waitcnt vmcnt(59)
	v_mul_f32_e32 v32, v32, v75
	v_fmac_f32_e32 v32, 0x3fb504f3, v120
	global_load_dword v120, v72, s[28:29] offset:-3904
	global_store_dword v72, v32, s[28:29] offset:-4032
	s_waitcnt vmcnt(60)
	v_mul_f32_e32 v33, v33, v75
	v_fmac_f32_e32 v33, 0x3fb504f3, v121
	global_load_dword v121, v72, s[28:29] offset:192
	global_store_dword v72, v33, s[28:29] offset:64
	s_waitcnt vmcnt(61)
	v_mul_f32_e32 v34, v34, v75
	v_fmac_f32_e32 v34, 0x3fb504f3, v122
	global_load_dword v122, v73, s[28:29] offset:-3904
	global_store_dword v73, v34, s[28:29] offset:-4032
	s_waitcnt vmcnt(62)
	v_mul_f32_e32 v35, v35, v75
	v_fmac_f32_e32 v35, 0x3fb504f3, v123
	global_load_dword v123, v73, s[28:29] offset:192
	global_store_dword v73, v35, s[28:29] offset:64
	s_waitcnt vmcnt(63)
	v_mul_f32_e32 v28, v28, v76
	v_fmac_f32_e32 v28, 0x3fb504f3, v78
	global_store_dword v66, v28, s[28:29] offset:-3968
	s_waitcnt vmcnt(62)
	v_mul_f32_e32 v29, v29, v76
	v_fmac_f32_e32 v29, 0x3fb504f3, v79
	global_store_dword v66, v29, s[28:29] offset:128
	s_waitcnt vmcnt(61)
	v_mul_f32_e32 v30, v30, v76
	v_fmac_f32_e32 v30, 0x3fb504f3, v82
	global_store_dword v67, v30, s[28:29] offset:-3968
	s_waitcnt vmcnt(60)
	v_mul_f32_e32 v31, v31, v76
	v_fmac_f32_e32 v31, 0x3fb504f3, v83
	global_store_dword v67, v31, s[28:29] offset:128
	s_waitcnt vmcnt(59)
	v_mul_f32_e32 v24, v24, v76
	v_fmac_f32_e32 v24, 0x3fb504f3, v91
	global_store_dword v68, v24, s[28:29] offset:-3968
	s_waitcnt vmcnt(58)
	v_mul_f32_e32 v25, v25, v76
	v_fmac_f32_e32 v25, 0x3fb504f3, v93
	global_store_dword v68, v25, s[28:29] offset:128
	s_waitcnt vmcnt(57)
	v_mul_f32_e32 v26, v26, v76
	v_fmac_f32_e32 v26, 0x3fb504f3, v94
	global_store_dword v69, v26, s[28:29] offset:-3968
	s_waitcnt vmcnt(56)
	v_mul_f32_e32 v27, v27, v76
	v_fmac_f32_e32 v27, 0x3fb504f3, v95
	global_store_dword v69, v27, s[28:29] offset:128
	s_waitcnt vmcnt(55)
	v_mul_f32_e32 v20, v20, v76
	v_fmac_f32_e32 v20, 0x3fb504f3, v97
	global_store_dword v70, v20, s[28:29] offset:-3968
	s_waitcnt vmcnt(54)
	v_mul_f32_e32 v21, v21, v76
	v_fmac_f32_e32 v21, 0x3fb504f3, v98
	global_store_dword v70, v21, s[28:29] offset:128
	s_waitcnt vmcnt(53)
	v_mul_f32_e32 v22, v22, v76
	v_fmac_f32_e32 v22, 0x3fb504f3, v99
	global_store_dword v71, v22, s[28:29] offset:-3968
	s_waitcnt vmcnt(52)
	v_mul_f32_e32 v23, v23, v76
	v_fmac_f32_e32 v23, 0x3fb504f3, v100
	global_store_dword v71, v23, s[28:29] offset:128
	s_waitcnt vmcnt(51)
	v_mul_f32_e32 v16, v16, v76
	v_fmac_f32_e32 v16, 0x3fb504f3, v101
	global_store_dword v72, v16, s[28:29] offset:-3968
	s_waitcnt vmcnt(50)
	v_mul_f32_e32 v17, v17, v76
	v_fmac_f32_e32 v17, 0x3fb504f3, v102
	global_store_dword v72, v17, s[28:29] offset:128
	s_waitcnt vmcnt(49)
	v_mul_f32_e32 v18, v18, v76
	v_fmac_f32_e32 v18, 0x3fb504f3, v103
	global_store_dword v73, v18, s[28:29] offset:-3968
	s_waitcnt vmcnt(48)
	v_mul_f32_e32 v19, v19, v76
	v_fmac_f32_e32 v19, 0x3fb504f3, v104
	global_store_dword v73, v19, s[28:29] offset:128
	s_waitcnt vmcnt(47)
	v_mul_f32_e32 v12, v12, v77
	v_fmac_f32_e32 v12, 0x3fb504f3, v105
	global_store_dword v66, v12, s[28:29] offset:-3904
	s_waitcnt vmcnt(46)
	v_mul_f32_e32 v13, v13, v77
	v_fmac_f32_e32 v13, 0x3fb504f3, v106
	global_store_dword v66, v13, s[28:29] offset:192
	s_waitcnt vmcnt(45)
	v_mul_f32_e32 v14, v14, v77
	v_fmac_f32_e32 v14, 0x3fb504f3, v107
	global_store_dword v67, v14, s[28:29] offset:-3904
	s_waitcnt vmcnt(44)
	v_mul_f32_e32 v15, v15, v77
	v_fmac_f32_e32 v15, 0x3fb504f3, v108
	global_store_dword v67, v15, s[28:29] offset:192
	s_waitcnt vmcnt(43)
	v_mul_f32_e32 v8, v8, v77
	v_fmac_f32_e32 v8, 0x3fb504f3, v109
	global_store_dword v68, v8, s[28:29] offset:-3904
	s_waitcnt vmcnt(42)
	v_mul_f32_e32 v9, v9, v77
	v_fmac_f32_e32 v9, 0x3fb504f3, v110
	global_store_dword v68, v9, s[28:29] offset:192
	s_waitcnt vmcnt(41)
	v_mul_f32_e32 v10, v10, v77
	v_fmac_f32_e32 v10, 0x3fb504f3, v111
	global_store_dword v69, v10, s[28:29] offset:-3904
	s_waitcnt vmcnt(40)
	v_mul_f32_e32 v11, v11, v77
	v_fmac_f32_e32 v11, 0x3fb504f3, v112
	global_store_dword v69, v11, s[28:29] offset:192
	s_waitcnt vmcnt(39)
	v_mul_f32_e32 v4, v4, v77
	v_fmac_f32_e32 v4, 0x3fb504f3, v116
	global_store_dword v70, v4, s[28:29] offset:-3904
	s_waitcnt vmcnt(38)
	v_mul_f32_e32 v5, v5, v77
	v_fmac_f32_e32 v5, 0x3fb504f3, v117
	global_store_dword v70, v5, s[28:29] offset:192
	s_waitcnt vmcnt(37)
	v_mul_f32_e32 v6, v6, v77
	v_fmac_f32_e32 v6, 0x3fb504f3, v118
	global_store_dword v71, v6, s[28:29] offset:-3904
	s_waitcnt vmcnt(36)
	v_mul_f32_e32 v7, v7, v77
	v_fmac_f32_e32 v7, 0x3fb504f3, v119
	global_store_dword v71, v7, s[28:29] offset:192
	s_waitcnt vmcnt(35)
	v_mul_f32_e32 v0, v0, v77
	v_fmac_f32_e32 v0, 0x3fb504f3, v120
	global_store_dword v72, v0, s[28:29] offset:-3904
	s_waitcnt vmcnt(34)
	v_mul_f32_e32 v1, v1, v77
	v_fmac_f32_e32 v1, 0x3fb504f3, v121
	global_store_dword v72, v1, s[28:29] offset:192
	s_waitcnt vmcnt(33)
	v_mul_f32_e32 v2, v2, v77
	v_fmac_f32_e32 v2, 0x3fb504f3, v122
	global_store_dword v73, v2, s[28:29] offset:-3904
	s_waitcnt vmcnt(32)
	v_mul_f32_e32 v3, v3, v77
	v_fmac_f32_e32 v3, 0x3fb504f3, v123
	global_store_dword v73, v3, s[28:29] offset:192
	s_cbranch_scc0 .LBB0_649
